# S5 chunk-carry scan (wave 0) rewritten: 2-deep FMA chain, LDS row prefetch, d16_hi writes; + s5_sample C loads hoisted; dead DPP-old movs -> s_nop
# speedup vs baseline: 1.1458x; 1.0048x over previous
.LBB0_445:
	v_add_u32_e32 v35, 0, v34
	ds_read_b128 v[36:39], v35
	ds_read_b128 v[40:43], v35 offset:64
	s_add_i32 s0, s0, -1
	v_add_u32_e32 v34, 0x2100, v34
	s_cmp_eq_u32 s0, 0
	s_waitcnt lgkmcnt(1)
	v_mfma_f32_16x16x32_bf16 v[36:39], v[36:39], v[0:3], 0
	s_waitcnt lgkmcnt(0)
	v_mfma_f32_16x16x32_bf16 v[36:39], v[40:43], v[4:7], v[36:39]
	ds_read_b128 v[40:43], v35 offset:128
	s_waitcnt lgkmcnt(0)
	v_mfma_f32_16x16x32_bf16 v[36:39], v[40:43], v[8:11], v[36:39]
	ds_read_b128 v[40:43], v35 offset:192
	s_waitcnt lgkmcnt(0)
	v_mfma_f32_16x16x32_bf16 v[36:39], v[40:43], v[12:15], v[36:39]
	ds_read_b128 v[40:43], v35 offset:256
	s_waitcnt lgkmcnt(0)
	v_mfma_f32_16x16x32_bf16 v[36:39], v[40:43], v[16:19], v[36:39]
	ds_read_b128 v[40:43], v35 offset:320
	s_waitcnt lgkmcnt(0)
	v_mfma_f32_16x16x32_bf16 v[36:39], v[40:43], v[20:23], v[36:39]
	ds_read_b128 v[40:43], v35 offset:384
	s_waitcnt lgkmcnt(0)
	v_mfma_f32_16x16x32_bf16 v[36:39], v[40:43], v[24:27], v[36:39]
	ds_read_b128 v[40:43], v35 offset:448
	v_add_u32_e32 v35, 0, v33
	v_add_u32_e32 v33, 0x2000, v33
	s_waitcnt lgkmcnt(0)
	v_mfma_f32_16x16x32_bf16 v[36:39], v[40:43], v[28:31], v[36:39]
	v_add_u32_e32 v40, 0x10a10, v35
	s_nop 6
	ds_write_b32 v40, v36
	v_add_u32_e32 v36, 0x10c10, v35
	ds_write_b32 v36, v37
	v_add_u32_e32 v36, 0x10e10, v35
	v_add_u32_e32 v35, 0x11010, v35
	ds_write_b32 v36, v38
	ds_write_b32 v35, v39
	s_cbranch_scc0 .LBB0_445
	s_ashr_i32 s0, s7, 5
	s_mul_i32 s1, s30, 0x30000
	s_add_u32 s18, s76, s1
	s_addc_u32 s19, s77, 0
	v_lshlrev_b32_e32 v0, 1, v32
	v_mov_b32_e32 v1, v105
	v_lshl_or_b32 v50, v112, 5, v109
	v_lshl_add_u64 v[48:49], s[18:19], 0, v[0:1]
	v_mad_i64_i32 v[44:45], s[18:19], v50, s5, v[48:49]
	v_or_b32_e32 v50, 16, v50
	v_mad_i64_i32 v[92:93], s[18:19], v50, s5, v[48:49]
	s_waitcnt lgkmcnt(0)
	s_barrier
	global_load_dwordx4 v[0:3], v[44:45], off
	global_load_dwordx4 v[4:7], v[44:45], off offset:64
	global_load_dwordx4 v[8:11], v[44:45], off offset:128
	global_load_dwordx4 v[12:15], v[44:45], off offset:192
	global_load_dwordx4 v[16:19], v[44:45], off offset:256
	global_load_dwordx4 v[20:23], v[44:45], off offset:320
	global_load_dwordx4 v[24:27], v[44:45], off offset:384
	global_load_dwordx4 v[28:31], v[44:45], off offset:448
	global_load_dwordx4 v[32:35], v[44:45], off offset:512
	global_load_dwordx4 v[36:39], v[44:45], off offset:576
	global_load_dwordx4 v[40:43], v[44:45], off offset:640
	s_nop 0
	global_load_dwordx4 v[44:47], v[44:45], off offset:704
	s_nop 0
	global_load_dwordx4 v[48:51], v[92:93], off
	global_load_dwordx4 v[52:55], v[92:93], off offset:64
	global_load_dwordx4 v[56:59], v[92:93], off offset:128
	global_load_dwordx4 v[60:63], v[92:93], off offset:192
	global_load_dwordx4 v[64:67], v[92:93], off offset:256
	global_load_dwordx4 v[68:71], v[92:93], off offset:320
	global_load_dwordx4 v[72:75], v[92:93], off offset:384
	global_load_dwordx4 v[76:79], v[92:93], off offset:448
	global_load_dwordx4 v[80:83], v[92:93], off offset:512
	global_load_dwordx4 v[84:87], v[92:93], off offset:576
	global_load_dwordx4 v[88:91], v[92:93], off offset:640
	s_nop 0
	global_load_dwordx4 v[92:95], v[92:93], off offset:704
	v_cmp_gt_u32_e32 vcc, 64, v96
	s_and_saveexec_b64 s[18:19], vcc
	s_cbranch_execz .LBB0_464
	s_lshl_b32 s1, s30, 7
	v_readlane_b32 s34, v250, 41
	v_lshl_or_b32 v98, v96, 1, s1
	v_mov_b32_e32 v99, v105
	v_readlane_b32 s35, v250, 42
	v_lshlrev_b32_e32 v116, 1, v115
	v_lshlrev_b32_e32 v117, 2, v96
	v_lshl_add_u64 v[98:99], v[98:99], 2, s[34:35]
	global_load_dwordx2 v[98:99], v[98:99], off
	v_mov_b32_e32 v108, 0
	s_mov_b32 s1, -4
	v_mov_b32_e32 v96, 0
	s_waitcnt vmcnt(0)
	v_pk_mov_b32 v[100:101], v[98:99], v[98:99] op_sel:[1,0]
	v_add_u32_e32 v117, 0x10a10, v117
	v_add_u32_e32 v116, 0x10a10, v116
	v_mov_b32_e32 v96, 0
	v_mov_b32_e32 v97, 0
	ds_read_b32 v100, v117
	ds_read_b32 v101, v117 offset:256
	ds_read_b32 v102, v117 offset:512
	ds_read_b32 v103, v117 offset:768
	ds_read_b32 v106, v117 offset:1024
	ds_read_b32 v107, v117 offset:1280
	ds_read_b32 v110, v117 offset:1536
	ds_read_b32 v111, v117 offset:1792
	s_mov_b32 s1, 16
	s_waitcnt lgkmcnt(0)
.Ls5car_loop:
	ds_read_b32 v118, v117 offset:2048
	ds_read_b32 v119, v117 offset:2304
	ds_read_b32 v120, v117 offset:2560
	ds_read_b32 v121, v117 offset:2816
	ds_read_b32 v122, v117 offset:3072
	ds_read_b32 v123, v117 offset:3328
	ds_read_b32 v124, v117 offset:3584
	ds_read_b32 v125, v117 offset:3840
	v_cvt_pk_bf16_f32 v108, v96, v97
	ds_write_b16 v116, v108
	ds_write_b16_d16_hi v116, v108 offset:128
	v_fmac_f32_e32 v100, v98, v96
	v_fmac_f32_e32 v101, v98, v97
	v_fma_f32 v100, -v99, v97, v100
	v_fma_f32 v101, v99, v96, v101
	v_cvt_pk_bf16_f32 v108, v100, v101
	ds_write_b16 v116, v108 offset:272
	ds_write_b16_d16_hi v116, v108 offset:400
	v_fmac_f32_e32 v102, v98, v100
	v_fmac_f32_e32 v103, v98, v101
	v_fma_f32 v102, -v99, v101, v102
	v_fma_f32 v103, v99, v100, v103
	v_cvt_pk_bf16_f32 v108, v102, v103
	ds_write_b16 v116, v108 offset:544
	ds_write_b16_d16_hi v116, v108 offset:672
	v_fmac_f32_e32 v106, v98, v102
	v_fmac_f32_e32 v107, v98, v103
	v_fma_f32 v106, -v99, v103, v106
	v_fma_f32 v107, v99, v102, v107
	v_cvt_pk_bf16_f32 v108, v106, v107
	ds_write_b16 v116, v108 offset:816
	ds_write_b16_d16_hi v116, v108 offset:944
	v_fmac_f32_e32 v110, v98, v106
	v_fmac_f32_e32 v111, v98, v107
	v_fma_f32 v96, -v99, v107, v110
	v_fma_f32 v97, v99, v106, v111
	s_waitcnt lgkmcnt(0)
	ds_read_b32 v100, v117 offset:4096
	ds_read_b32 v101, v117 offset:4352
	ds_read_b32 v102, v117 offset:4608
	ds_read_b32 v103, v117 offset:4864
	ds_read_b32 v106, v117 offset:5120
	ds_read_b32 v107, v117 offset:5376
	ds_read_b32 v110, v117 offset:5632
	ds_read_b32 v111, v117 offset:5888
	v_cvt_pk_bf16_f32 v108, v96, v97
	ds_write_b16 v116, v108 offset:1088
	ds_write_b16_d16_hi v116, v108 offset:1216
	v_fmac_f32_e32 v118, v98, v96
	v_fmac_f32_e32 v119, v98, v97
	v_fma_f32 v118, -v99, v97, v118
	v_fma_f32 v119, v99, v96, v119
	v_cvt_pk_bf16_f32 v108, v118, v119
	ds_write_b16 v116, v108 offset:1360
	ds_write_b16_d16_hi v116, v108 offset:1488
	v_fmac_f32_e32 v120, v98, v118
	v_fmac_f32_e32 v121, v98, v119
	v_fma_f32 v120, -v99, v119, v120
	v_fma_f32 v121, v99, v118, v121
	v_cvt_pk_bf16_f32 v108, v120, v121
	ds_write_b16 v116, v108 offset:1632
	ds_write_b16_d16_hi v116, v108 offset:1760
	v_fmac_f32_e32 v122, v98, v120
	v_fmac_f32_e32 v123, v98, v121
	v_fma_f32 v122, -v99, v121, v122
	v_fma_f32 v123, v99, v120, v123
	v_cvt_pk_bf16_f32 v108, v122, v123
	ds_write_b16 v116, v108 offset:1904
	ds_write_b16_d16_hi v116, v108 offset:2032
	v_fmac_f32_e32 v124, v98, v122
	v_fmac_f32_e32 v125, v98, v123
	v_fma_f32 v96, -v99, v123, v124
	v_fma_f32 v97, v99, v122, v125
	v_add_u32_e32 v117, 0x1000, v117
	v_add_u32_e32 v116, 0x880, v116
	s_sub_i32 s1, s1, 1
	s_waitcnt lgkmcnt(0)
	s_cmp_lg_u32 s1, 0
	s_cbranch_scc1 .Ls5car_loop
	v_cvt_pk_bf16_f32 v108, v96, v97
	ds_write_b16 v116, v108
	ds_write_b16_d16_hi v116, v108 offset:128
	v_fmac_f32_e32 v100, v98, v96
	v_fmac_f32_e32 v101, v98, v97
	v_fma_f32 v102, -v99, v97, v100
	v_fma_f32 v103, v99, v96, v101
	v_mov_b32_e32 v96, v102
	v_mov_b32_e32 v97, v103
	s_branch .LBB0_463

.LBB0_538:
	v_ashrrev_i32_e32 v8, 5, v3
	v_ashrrev_i32_e32 v9, 31, v8
	v_and_b32_e32 v22, 31, v3
	s_waitcnt lgkmcnt(0)
	v_lshlrev_b64 v[12:13], 5, v[8:9]
	v_or_b32_e32 v12, v12, v22
	v_lshlrev_b64 v[10:11], 5, v[12:13]
	v_lshl_add_u64 v[10:11], s[24:25], 0, v[10:11]
	global_load_dwordx4 v[24:27], v[10:11], off offset:16
	global_load_dwordx4 v[28:31], v[10:11], off
	v_lshl_or_b32 v96, v22, 12, v21
	global_load_dword v64, v96, s[8:9]
	global_load_dword v80, v96, s[10:11]
	global_load_dword v65, v96, s[8:9] offset:256
	global_load_dword v81, v96, s[10:11] offset:256
	global_load_dword v66, v96, s[8:9] offset:512
	global_load_dword v82, v96, s[10:11] offset:512
	global_load_dword v67, v96, s[8:9] offset:768
	global_load_dword v83, v96, s[10:11] offset:768
	global_load_dword v68, v96, s[8:9] offset:1024
	global_load_dword v84, v96, s[10:11] offset:1024
	global_load_dword v69, v96, s[8:9] offset:1280
	global_load_dword v85, v96, s[10:11] offset:1280
	global_load_dword v70, v96, s[8:9] offset:1536
	global_load_dword v86, v96, s[10:11] offset:1536
	global_load_dword v71, v96, s[8:9] offset:1792
	global_load_dword v87, v96, s[10:11] offset:1792
	global_load_dword v72, v96, s[8:9] offset:2048
	global_load_dword v88, v96, s[10:11] offset:2048
	global_load_dword v73, v96, s[8:9] offset:2304
	global_load_dword v89, v96, s[10:11] offset:2304
	global_load_dword v74, v96, s[8:9] offset:2560
	global_load_dword v90, v96, s[10:11] offset:2560
	global_load_dword v75, v96, s[8:9] offset:2816
	global_load_dword v91, v96, s[10:11] offset:2816
	global_load_dword v76, v96, s[8:9] offset:3072
	global_load_dword v92, v96, s[10:11] offset:3072
	global_load_dword v77, v96, s[8:9] offset:3328
	global_load_dword v93, v96, s[10:11] offset:3328
	global_load_dword v78, v96, s[8:9] offset:3584
	global_load_dword v94, v96, s[10:11] offset:3584
	global_load_dword v79, v96, s[8:9] offset:3840
	global_load_dword v95, v96, s[10:11] offset:3840
	v_readlane_b32 s4, v250, 39
	v_readlane_b32 s5, v250, 40
	s_waitcnt vmcnt(33)
	v_lshlrev_b32_e32 v48, 16, v24
	v_and_b32_e32 v49, 0xffff0000, v24
	v_lshl_or_b32 v24, v22, 6, v2
	v_lshlrev_b32_e32 v14, 3, v24
	v_lshlrev_b32_e32 v56, 7, v24
	s_waitcnt vmcnt(32)
	v_lshlrev_b32_e32 v4, 16, v28
	v_and_b32_e32 v23, 0xffff0000, v28
	v_lshlrev_b32_e32 v32, 16, v29
	v_and_b32_e32 v33, 0xffff0000, v29
	v_lshlrev_b32_e32 v44, 16, v30
	v_and_b32_e32 v45, 0xffff0000, v30
	v_lshlrev_b32_e32 v46, 16, v31
	v_and_b32_e32 v47, 0xffff0000, v31
	v_lshlrev_b32_e32 v50, 16, v25
	v_and_b32_e32 v51, 0xffff0000, v25
	v_lshlrev_b32_e32 v52, 16, v26
	v_and_b32_e32 v53, 0xffff0000, v26
	v_lshlrev_b32_e32 v54, 16, v27
	v_and_b32_e32 v55, 0xffff0000, v27
	global_load_dwordx2 v[14:15], v14, s[4:5]
	s_nop 0
	global_load_dwordx4 v[24:27], v56, s[2:3] offset:48
	global_load_dwordx4 v[28:31], v56, s[2:3] offset:32
	global_load_dwordx4 v[36:39], v56, s[2:3] offset:16
	global_load_dwordx4 v[40:43], v56, s[2:3]
	s_mov_b32 s4, 0x42f0000
	s_waitcnt vmcnt(0)
	v_fma_f32 v57, v40, v4, 0
	v_fma_f32 v58, v41, v4, 0
	v_fmac_f32_e32 v57, v42, v23
	v_fmac_f32_e32 v58, v43, v23
	v_fmac_f32_e32 v57, v36, v32
	v_fmac_f32_e32 v58, v37, v32
	v_fmac_f32_e32 v57, v38, v33
	v_fmac_f32_e32 v58, v39, v33
	v_fmac_f32_e32 v57, v28, v44
	v_fmac_f32_e32 v58, v29, v44
	v_fmac_f32_e32 v57, v30, v45
	v_fmac_f32_e32 v58, v31, v45
	v_fmac_f32_e32 v57, v24, v46
	v_fmac_f32_e32 v58, v25, v46
	v_fmac_f32_e32 v57, v26, v47
	v_fmac_f32_e32 v58, v27, v47
	global_load_dwordx4 v[24:27], v56, s[2:3] offset:112
	global_load_dwordx4 v[28:31], v56, s[2:3] offset:96
	global_load_dwordx4 v[36:39], v56, s[2:3] offset:80
	global_load_dwordx4 v[40:43], v56, s[2:3] offset:64
	s_waitcnt vmcnt(0)
	v_fmac_f32_e32 v57, v40, v48
	v_fmac_f32_e32 v58, v41, v48
	v_fmac_f32_e32 v57, v42, v49
	v_fmac_f32_e32 v58, v43, v49
	v_fmac_f32_e32 v57, v36, v50
	v_fmac_f32_e32 v58, v37, v50
	v_fmac_f32_e32 v57, v38, v51
	v_fmac_f32_e32 v58, v39, v51
	v_fmac_f32_e32 v57, v28, v52
	v_fmac_f32_e32 v58, v29, v52
	v_fmac_f32_e32 v57, v30, v53
	v_fmac_f32_e32 v58, v31, v53
	v_fmac_f32_e32 v57, v24, v54
	v_fmac_f32_e32 v58, v25, v54
	v_lshlrev_b64 v[24:25], 8, v[12:13]
	v_lshl_or_b32 v24, v2, 2, v24
	v_lshl_add_u64 v[12:13], s[76:77], 0, v[24:25]
	global_load_dword v23, v[12:13], off
	v_lshl_add_u64 v[12:13], s[78:79], 0, v[24:25]
	global_load_dword v12, v[12:13], off
	v_fmac_f32_e32 v57, v26, v55
	v_fmac_f32_e32 v58, v27, v55
	v_lshl_or_b32 v13, v22, 12, v21
	s_waitcnt vmcnt(0)
	v_mul_f32_e32 v4, v15, v12
	v_mul_f32_e32 v12, v14, v12
	v_fma_f32 v4, v14, v23, -v4
	v_fmac_f32_e32 v12, v15, v23
	v_lshl_add_u64 v[14:15], s[90:91], 0, v[24:25]
	v_add_co_u32_e32 v24, vcc, s4, v14
	s_mov_b32 s4, 0x43f0000
	s_nop 0
	v_addc_co_u32_e32 v25, vcc, 0, v15, vcc
	v_add_co_u32_e32 v14, vcc, s4, v14
	v_add_f32_e32 v4, v57, v4
	v_add_f32_e32 v12, v58, v12
	v_addc_co_u32_e32 v15, vcc, 0, v15, vcc
	global_store_dword v[24:25], v4, off
	global_store_dword v[14:15], v12, off
	v_mul_f32_e32 v15, v12, v80
	v_fma_f32 v14, v4, v64, -v15
	v_mul_f32_e32 v23, v12, v81
	v_fma_f32 v15, v4, v65, -v23
	v_mul_f32_e32 v24, v12, v82
	v_fma_f32 v23, v4, v66, -v24
	v_mul_f32_e32 v25, v12, v83
	v_fma_f32 v24, v4, v67, -v25
	v_mul_f32_e32 v26, v12, v84
	v_fma_f32 v25, v4, v68, -v26
	v_mul_f32_e32 v27, v12, v85
	v_fma_f32 v26, v4, v69, -v27
	v_mul_f32_e32 v28, v12, v86
	v_fma_f32 v27, v4, v70, -v28
	v_mul_f32_e32 v29, v12, v87
	v_fma_f32 v28, v4, v71, -v29
	v_mul_f32_e32 v30, v12, v88
	v_fma_f32 v29, v4, v72, -v30
	v_mul_f32_e32 v31, v12, v89
	v_fma_f32 v30, v4, v73, -v31
	v_mul_f32_e32 v32, v12, v90
	v_fma_f32 v31, v4, v74, -v32
	v_mul_f32_e32 v33, v12, v91
	v_fma_f32 v32, v4, v75, -v33
	v_mul_f32_e32 v36, v12, v92
	v_fma_f32 v33, v4, v76, -v36
	v_mul_f32_e32 v37, v12, v93
	v_fma_f32 v36, v4, v77, -v37
	v_mul_f32_e32 v38, v12, v94
	v_fma_f32 v37, v4, v78, -v38
	v_mul_f32_e32 v12, v12, v95
	v_cndmask_b32_e64 v13, v14, v29, s[38:39]
	ds_bpermute_b32 v13, v7, v13
	v_fma_f32 v4, v4, v79, -v12
	v_cndmask_b32_e64 v12, v29, v14, s[38:39]
	v_cndmask_b32_e64 v14, v15, v30, s[38:39]
	ds_bpermute_b32 v14, v7, v14
	s_waitcnt lgkmcnt(1)
	v_add_f32_e32 v12, v12, v13
	v_cndmask_b32_e64 v13, v30, v15, s[38:39]
	v_cndmask_b32_e64 v15, v23, v31, s[38:39]
	ds_bpermute_b32 v15, v7, v15
	s_waitcnt lgkmcnt(1)
	v_add_f32_e32 v13, v13, v14
	v_cndmask_b32_e64 v14, v31, v23, s[38:39]
	v_cndmask_b32_e64 v23, v24, v32, s[38:39]
	ds_bpermute_b32 v23, v7, v23
	s_waitcnt lgkmcnt(1)
	v_add_f32_e32 v14, v14, v15
	v_cndmask_b32_e64 v15, v32, v24, s[38:39]
	v_cndmask_b32_e64 v24, v25, v33, s[38:39]
	ds_bpermute_b32 v24, v7, v24
	s_waitcnt lgkmcnt(1)
	v_add_f32_e32 v15, v15, v23
	v_cndmask_b32_e64 v23, v33, v25, s[38:39]
	v_cndmask_b32_e64 v25, v26, v36, s[38:39]
	ds_bpermute_b32 v25, v7, v25
	s_waitcnt lgkmcnt(1)
	v_add_f32_e32 v23, v23, v24
	v_cndmask_b32_e64 v24, v36, v26, s[38:39]
	v_cndmask_b32_e64 v26, v27, v37, s[38:39]
	ds_bpermute_b32 v26, v7, v26
	s_waitcnt lgkmcnt(1)
	v_add_f32_e32 v24, v24, v25
	v_cndmask_b32_e64 v25, v37, v27, s[38:39]
	s_waitcnt lgkmcnt(0)
	v_add_f32_e32 v25, v25, v26
	v_cndmask_b32_e64 v26, v4, v28, s[38:39]
	v_cndmask_b32_e64 v4, v28, v4, s[38:39]
	ds_bpermute_b32 v4, v7, v4
	s_waitcnt lgkmcnt(0)
	v_add_f32_e32 v4, v26, v4
	v_cndmask_b32_e64 v26, v23, v12, s[40:41]
	v_cndmask_b32_e64 v12, v12, v23, s[40:41]
	v_cndmask_b32_e64 v23, v24, v13, s[40:41]
	v_cndmask_b32_e64 v13, v13, v24, s[40:41]
	ds_bpermute_b32 v13, v16, v13
	ds_bpermute_b32 v12, v16, v12
	s_waitcnt lgkmcnt(1)
	v_add_f32_e32 v13, v23, v13
	v_cndmask_b32_e64 v23, v25, v14, s[40:41]
	v_cndmask_b32_e64 v14, v14, v25, s[40:41]
	ds_bpermute_b32 v14, v16, v14
	s_waitcnt lgkmcnt(1)
	v_add_f32_e32 v12, v26, v12
	s_waitcnt lgkmcnt(0)
	v_add_f32_e32 v14, v23, v14
	v_cndmask_b32_e64 v23, v4, v15, s[40:41]
	v_cndmask_b32_e64 v4, v15, v4, s[40:41]
	ds_bpermute_b32 v4, v16, v4
	v_cndmask_b32_e64 v15, v14, v12, s[42:43]
	v_cndmask_b32_e64 v12, v12, v14, s[42:43]
	ds_bpermute_b32 v12, v17, v12
	s_waitcnt lgkmcnt(1)
	v_add_f32_e32 v4, v23, v4
	v_cndmask_b32_e64 v14, v4, v13, s[42:43]
	v_cndmask_b32_e64 v4, v13, v4, s[42:43]
	ds_bpermute_b32 v4, v17, v4
	s_waitcnt lgkmcnt(1)
	v_add_f32_e32 v12, v15, v12
	s_waitcnt lgkmcnt(0)
	v_add_f32_e32 v4, v14, v4
	v_cndmask_b32_e64 v13, v4, v12, s[44:45]
	v_cndmask_b32_e64 v4, v12, v4, s[44:45]
	ds_bpermute_b32 v4, v18, v4
	s_waitcnt lgkmcnt(0)
	v_add_f32_e32 v4, v13, v4
	ds_bpermute_b32 v12, v19, v4
	s_waitcnt lgkmcnt(0)
	v_add_f32_e32 v12, v4, v12
	ds_bpermute_b32 v13, v20, v12
	s_and_saveexec_b64 s[28:29], s[46:47]
	s_cbranch_execz .LBB0_537
	v_lshlrev_b32_e32 v4, 1, v6
	v_lshl_add_u64 v[10:11], v[10:11], 0, v[4:5]
	global_load_ushort v11, v[10:11], off
	v_lshlrev_b32_e32 v10, 2, v6
	v_lshl_or_b32 v10, v22, 6, v10
	global_load_dword v14, v10, s[12:13]
	s_waitcnt lgkmcnt(0)
	v_add_f32_e32 v12, v12, v13
	v_lshlrev_b64 v[8:9], 10, v[8:9]
	v_lshlrev_b32_e32 v10, 5, v22
	v_lshl_add_u64 v[8:9], s[68:69], 0, v[8:9]
	s_waitcnt vmcnt(1)
	v_lshlrev_b32_e32 v11, 16, v11
	s_waitcnt vmcnt(0)
	v_fmac_f32_e32 v12, v14, v11
	v_mul_f32_e32 v11, 0x3d372713, v12
	v_mul_f32_e32 v11, v12, v11
	v_fma_f32 v11, v12, v11, v12
	v_mul_f32_e32 v11, 0x3fcc422a, v11
	v_mul_f32_e32 v11, 0xbfb8aa3b, v11
	v_exp_f32_e32 v13, v11
	v_mov_b32_e32 v11, v5
	v_lshl_add_u64 v[8:9], v[8:9], 0, v[10:11]
	v_lshl_add_u64 v[8:9], v[8:9], 0, v[4:5]
	v_add_f32_e32 v10, 1.0, v13
	v_rcp_f32_e32 v10, v10
	v_add_co_u32_e32 v8, vcc, 0x1020000, v8
	v_mul_f32_e32 v4, v12, v10
	s_nop 0
	v_addc_co_u32_e32 v9, vcc, 0, v9, vcc
	v_cvt_pk_bf16_f32 v4, v4, v5
	global_store_short v[8:9], v4, off
	s_branch .LBB0_537

.LBB0_934:
	v_lshl_or_b32 v210, s1, 7, v187
	v_ashrrev_i32_e32 v211, 31, v210
	v_readlane_b32 s16, v250, 23
	v_lshlrev_b64 v[212:213], 2, v[210:211]
	v_readlane_b32 s20, v250, 27
	v_readlane_b32 s21, v250, 28
	v_readlane_b32 s22, v250, 29
	v_readlane_b32 s23, v250, 30
	v_lshl_add_u64 v[40:41], s[20:21], 0, v[212:213]
	global_load_dwordx4 v[88:91], v[40:41], off offset:16
	global_load_dwordx4 v[92:95], v[40:41], off
	v_lshl_add_u64 v[40:41], s[60:61], 0, v[212:213]
	v_readlane_b32 s24, v250, 31
	v_readlane_b32 s25, v250, 32
	global_load_dwordx4 v[80:83], v[40:41], off offset:16
	global_load_dwordx4 v[56:59], v[40:41], off
	v_lshl_add_u64 v[40:41], s[22:23], 0, v[212:213]
	global_load_dwordx4 v[48:51], v[40:41], off offset:16
	global_load_dwordx4 v[72:75], v[40:41], off
	v_lshl_add_u64 v[40:41], s[36:37], 0, v[212:213]
	v_lshl_add_u64 v[52:53], s[58:59], 0, v[212:213]
	v_lshl_add_u64 v[76:77], s[24:25], 0, v[212:213]
	global_load_dwordx4 v[44:47], v[40:41], off offset:16
	global_load_dwordx4 v[68:71], v[40:41], off
	s_nop 0
	global_load_dwordx4 v[40:43], v[52:53], off offset:16
	global_load_dwordx4 v[60:63], v[52:53], off
	s_nop 0
	global_load_dwordx4 v[52:55], v[76:77], off offset:16
	s_nop 0
	global_load_dwordx4 v[76:79], v[76:77], off
	v_readlane_b32 s30, v250, 37
	s_lshl_b32 s0, s0, 2
	s_add_i32 s30, s0, s8
	v_lshl_or_b32 v227, s30, 6, v200
	v_mul_hi_i32 v198, v227, s14
	v_lshrrev_b32_e32 v214, 31, v198
	v_ashrrev_i32_e32 v198, 7, v198
	v_add_u32_e32 v214, v198, v214
	v_mad_i32_i24 v244, v214, s15, v227
	v_ashrrev_i32_e32 v215, 31, v214
	v_add_u32_e32 v198, 0xfffff7f2, v244
	v_lshl_add_u64 v[214:215], v[214:215], 1, v[198:199]
	v_mad_u64_u32 v[216:217], s[0:1], v214, s39, 0
	v_mad_i32_i24 v217, v215, s39, v217
	s_nop 7
	v_lshl_add_u64 v[214:215], s[62:63], 0, v[216:217]
	v_cmp_lt_i32_e32 vcc, s38, v244
	v_lshl_add_u64 v[216:217], v[210:211], 2, v[214:215]
	v_readlane_b32 s17, v250, 24
	v_readlane_b32 s18, v250, 25
	v_readlane_b32 s19, v250, 26
	v_readlane_b32 s26, v250, 33
	v_readlane_b32 s27, v250, 34
	v_readlane_b32 s28, v250, 35
	v_readlane_b32 s29, v250, 36
	v_readlane_b32 s31, v250, 38
	s_waitcnt vmcnt(0)
	v_pk_add_f32 v[174:175], v[174:175], v[94:95]
	v_pk_add_f32 v[172:173], v[172:173], v[92:93]
	s_nop 0
	v_mov_b32_dpp v230, v174 row_ror:1 row_mask:0xf bank_mask:0xf
	v_mov_b32_dpp v231, v175 row_ror:1 row_mask:0xf bank_mask:0xf
	v_mov_b32_dpp v228, v172 row_ror:1 row_mask:0xf bank_mask:0xf
	v_mov_b32_dpp v229, v173 row_ror:1 row_mask:0xf bank_mask:0xf
	v_mov_b32_dpp v232, v172 row_ror:2 row_mask:0xf bank_mask:0xf
	v_mov_b32_dpp v233, v173 row_ror:2 row_mask:0xf bank_mask:0xf
	v_mov_b32_dpp v234, v174 row_ror:2 row_mask:0xf bank_mask:0xf
	v_mov_b32_dpp v235, v175 row_ror:2 row_mask:0xf bank_mask:0xf
	s_and_saveexec_b64 s[0:1], vcc
	s_cbranch_execz .LBB0_936
	global_store_dwordx4 v[216:217], v[172:175], off

.LBB0_938:
	s_or_b64 exec, exec, s[0:1]
	v_pk_add_f32 v[170:171], v[170:171], v[90:91]
	v_pk_add_f32 v[168:169], v[168:169], v[88:89]
	s_nop 7
	v_mov_b32_dpp v236, v168 row_ror:1 row_mask:0xf bank_mask:0xf
	v_mov_b32_dpp v237, v169 row_ror:1 row_mask:0xf bank_mask:0xf
	v_mov_b32_dpp v238, v170 row_ror:1 row_mask:0xf bank_mask:0xf
	v_mov_b32_dpp v240, v171 row_ror:1 row_mask:0xf bank_mask:0xf
	v_mov_b32_dpp v239, v168 row_ror:2 row_mask:0xf bank_mask:0xf
	v_mov_b32_dpp v241, v169 row_ror:2 row_mask:0xf bank_mask:0xf
	v_mov_b32_dpp v242, v170 row_ror:2 row_mask:0xf bank_mask:0xf
	v_mov_b32_dpp v243, v171 row_ror:2 row_mask:0xf bank_mask:0xf
	s_and_saveexec_b64 s[0:1], vcc
	s_cbranch_execz .LBB0_940
	global_store_dwordx4 v[216:217], v[168:171], off offset:16

.LBB0_942:
	s_or_b64 exec, exec, s[0:1]
	v_cmp_eq_u32_e32 vcc, 0, v244
	v_cndmask_b32_e64 v198, 0, v232, s[44:45]
	v_cndmask_b32_e64 v245, 0, v233, s[44:45]
	s_or_b64 s[0:1], s[42:43], vcc
	v_cmp_gt_i32_e32 vcc, 2, v244
	v_cndmask_b32_e64 v220, 0, v234, s[44:45]
	v_cndmask_b32_e64 v221, 0, v235, s[44:45]
	v_cndmask_b32_e64 v245, v245, 0, vcc
	v_cndmask_b32_e64 v244, v198, 0, vcc
	v_cndmask_b32_e64 v217, v229, 0, s[0:1]
	v_cndmask_b32_e64 v216, v228, 0, s[0:1]
	v_cndmask_b32_e64 v221, v221, 0, vcc
	v_cndmask_b32_e64 v220, v220, 0, vcc
	v_pk_fma_f32 v[244:245], v[72:73], v[244:245], v[76:77]
	v_cndmask_b32_e64 v219, v231, 0, s[0:1]
	v_cndmask_b32_e64 v218, v230, 0, s[0:1]
	v_pk_fma_f32 v[220:221], v[74:75], v[220:221], v[78:79]
	v_pk_fma_f32 v[216:217], v[68:69], v[216:217], v[244:245]
	v_pk_fma_f32 v[218:219], v[70:71], v[218:219], v[220:221]
	v_pk_fma_f32 v[172:173], v[172:173], v[60:61], v[216:217]
	v_pk_fma_f32 v[174:175], v[174:175], v[62:63], v[218:219]
	v_pk_mul_f32 v[218:219], v[172:173], v[172:173]
	v_mov_b64_e32 v[220:221], s[70:71]
	v_pk_mul_f32 v[216:217], v[174:175], v[174:175]
	v_pk_fma_f32 v[218:219], v[218:219], s[68:69], v[220:221] op_sel_hi:[1,0,0] neg_lo:[1,0,0] neg_hi:[1,0,0]
	v_pk_fma_f32 v[216:217], v[216:217], s[68:69], v[220:221] op_sel_hi:[1,0,0] neg_lo:[1,0,0] neg_hi:[1,0,0]
	v_pk_mul_f32 v[218:219], v[172:173], v[218:219]
	v_pk_mul_f32 v[216:217], v[174:175], v[216:217]
	v_exp_f32_e32 v218, v218
	v_exp_f32_e32 v219, v219
	v_exp_f32_e32 v216, v216
	v_exp_f32_e32 v217, v217
	v_cndmask_b32_e64 v198, 0, v239, s[44:45]
	v_pk_add_f32 v[218:219], v[218:219], 1.0 op_sel_hi:[1,0]
	v_cndmask_b32_e64 v244, 0, v241, s[44:45]
	v_rcp_f32_e32 v218, v218
	v_rcp_f32_e32 v219, v219
	v_pk_add_f32 v[216:217], v[216:217], 1.0 op_sel_hi:[1,0]
	v_cndmask_b32_e64 v245, v244, 0, vcc
	v_rcp_f32_e32 v216, v216
	v_rcp_f32_e32 v217, v217
	v_pk_mul_f32 v[172:173], v[172:173], v[218:219]
	v_cndmask_b32_e64 v218, 0, v242, s[44:45]
	v_cndmask_b32_e64 v219, 0, v243, s[44:45]
	v_cndmask_b32_e64 v244, v198, 0, vcc
	v_pk_mul_f32 v[164:165], v[164:165], v[172:173]
	v_pk_mul_f32 v[172:173], v[174:175], v[216:217]
	v_cndmask_b32_e64 v175, v237, 0, s[0:1]
	v_cndmask_b32_e64 v174, v236, 0, s[0:1]
	v_cndmask_b32_e64 v219, v219, 0, vcc
	v_cndmask_b32_e64 v218, v218, 0, vcc
	v_pk_fma_f32 v[244:245], v[48:49], v[244:245], v[52:53]
	v_cndmask_b32_e64 v217, v240, 0, s[0:1]
	v_cndmask_b32_e64 v216, v238, 0, s[0:1]
	v_pk_fma_f32 v[218:219], v[50:51], v[218:219], v[54:55]
	v_pk_fma_f32 v[174:175], v[44:45], v[174:175], v[244:245]
	v_pk_fma_f32 v[216:217], v[46:47], v[216:217], v[218:219]
	v_pk_fma_f32 v[168:169], v[168:169], v[40:41], v[174:175]
	v_pk_fma_f32 v[170:171], v[170:171], v[42:43], v[216:217]
	v_pk_mul_f32 v[216:217], v[168:169], v[168:169]
	v_pk_mul_f32 v[174:175], v[170:171], v[170:171]
	v_pk_fma_f32 v[216:217], v[216:217], s[68:69], v[220:221] op_sel_hi:[1,0,0] neg_lo:[1,0,0] neg_hi:[1,0,0]
	v_pk_fma_f32 v[174:175], v[174:175], s[68:69], v[220:221] op_sel_hi:[1,0,0] neg_lo:[1,0,0] neg_hi:[1,0,0]
	v_pk_mul_f32 v[216:217], v[168:169], v[216:217]
	v_pk_mul_f32 v[174:175], v[170:171], v[174:175]
	v_exp_f32_e32 v216, v216
	v_exp_f32_e32 v217, v217
	v_exp_f32_e32 v174, v174
	v_exp_f32_e32 v175, v175
	v_or_b32_e32 v218, 16, v227
	v_pk_add_f32 v[216:217], v[216:217], 1.0 op_sel_hi:[1,0]
	v_pk_mul_f32 v[166:167], v[166:167], v[172:173]
	v_rcp_f32_e32 v216, v216
	v_rcp_f32_e32 v217, v217
	v_pk_add_f32 v[174:175], v[174:175], 1.0 op_sel_hi:[1,0]
	v_pk_add_f32 v[158:159], v[158:159], v[94:95]
	v_rcp_f32_e32 v174, v174
	v_rcp_f32_e32 v175, v175
	v_pk_mul_f32 v[168:169], v[168:169], v[216:217]
	v_pk_add_f32 v[156:157], v[156:157], v[92:93]
	v_pk_mul_f32 v[168:169], v[160:161], v[168:169]
	v_pk_mul_f32 v[160:161], v[170:171], v[174:175]
	s_nop 0
	v_pk_mul_f32 v[170:171], v[162:163], v[160:161]
	v_cvt_pk_bf16_f32 v160, v164, v165
	v_mov_b64_e32 v[164:165], s[86:87]
	v_mad_i64_i32 v[164:165], s[0:1], v227, s40, v[164:165]
	v_lshl_add_u64 v[164:165], v[210:211], 1, v[164:165]
	v_cvt_pk_bf16_f32 v161, v166, v167
	v_cvt_pk_bf16_f32 v162, v168, v169
	v_cvt_pk_bf16_f32 v163, v170, v171
	global_store_dwordx4 v[164:165], v[160:163], off
	s_nop 1
	v_mul_hi_i32 v160, v218, s14
	v_lshrrev_b32_e32 v161, 31, v160
	v_ashrrev_i32_e32 v160, 7, v160
	v_add_u32_e32 v160, v160, v161
	v_mad_i32_i24 v219, v160, s15, v218
	v_ashrrev_i32_e32 v161, 31, v160
	v_add_u32_e32 v198, 0xfffff7f2, v219
	v_lshl_add_u64 v[160:161], v[160:161], 1, v[198:199]
	v_mad_u64_u32 v[162:163], s[0:1], v160, s39, 0
	v_mad_i32_i24 v163, v161, s39, v163
	s_nop 4
	v_lshl_add_u64 v[160:161], s[62:63], 0, v[162:163]
	v_cmp_lt_i32_e32 vcc, s38, v219
	v_mov_b32_dpp v170, v156 row_ror:1 row_mask:0xf bank_mask:0xf
	v_mov_b32_dpp v171, v157 row_ror:1 row_mask:0xf bank_mask:0xf
	v_mov_b32_dpp v172, v158 row_ror:1 row_mask:0xf bank_mask:0xf
	v_mov_b32_dpp v174, v159 row_ror:1 row_mask:0xf bank_mask:0xf
	v_mov_b32_dpp v173, v156 row_ror:2 row_mask:0xf bank_mask:0xf
	v_mov_b32_dpp v175, v157 row_ror:2 row_mask:0xf bank_mask:0xf
	v_mov_b32_dpp v216, v158 row_ror:2 row_mask:0xf bank_mask:0xf
	v_mov_b32_dpp v217, v159 row_ror:2 row_mask:0xf bank_mask:0xf
	v_lshl_add_u64 v[160:161], v[210:211], 2, v[160:161]
	s_and_saveexec_b64 s[0:1], vcc
	s_cbranch_execz .LBB0_944
	global_store_dwordx4 v[160:161], v[156:159], off
.LBB0_944:
	s_or_b64 exec, exec, s[0:1]
	v_pk_add_f32 v[154:155], v[154:155], v[90:91]
	v_pk_add_f32 v[152:153], v[152:153], v[88:89]
	s_nop 7
	v_mov_b32_dpp v162, v152 row_ror:1 row_mask:0xf bank_mask:0xf
	v_mov_b32_dpp v163, v153 row_ror:1 row_mask:0xf bank_mask:0xf
	v_mov_b32_dpp v164, v154 row_ror:1 row_mask:0xf bank_mask:0xf
	v_mov_b32_dpp v166, v155 row_ror:1 row_mask:0xf bank_mask:0xf
	v_mov_b32_dpp v165, v152 row_ror:2 row_mask:0xf bank_mask:0xf
	v_mov_b32_dpp v167, v153 row_ror:2 row_mask:0xf bank_mask:0xf
	v_mov_b32_dpp v168, v154 row_ror:2 row_mask:0xf bank_mask:0xf
	v_mov_b32_dpp v169, v155 row_ror:2 row_mask:0xf bank_mask:0xf
	s_and_saveexec_b64 s[0:1], vcc
	s_cbranch_execz .LBB0_946
	global_store_dwordx4 v[160:161], v[152:155], off offset:16
.LBB0_946:
	s_or_b64 exec, exec, s[0:1]
	v_cmp_eq_u32_e64 s[52:53], 0, v219
	v_cmp_gt_i32_e32 vcc, 2, v219
	v_cndmask_b32_e64 v198, v172, v230, s[42:43]
	v_cndmask_b32_e64 v219, v174, v231, s[42:43]
	v_cndmask_b32_e64 v230, v232, v173, s[44:45]
	v_cndmask_b32_e64 v231, v233, v175, s[44:45]
	v_cndmask_b32_e64 v160, v170, v228, s[42:43]
	v_cndmask_b32_e64 v161, v171, v229, s[42:43]
	v_cndmask_b32_e64 v228, v234, v216, s[44:45]
	v_cndmask_b32_e64 v229, v235, v217, s[44:45]
	v_cndmask_b32_e64 v231, v231, 0, vcc
	v_cndmask_b32_e64 v230, v230, 0, vcc
	v_cndmask_b32_e64 v161, v161, 0, s[52:53]
	v_cndmask_b32_e64 v160, v160, 0, s[52:53]
	v_cndmask_b32_e64 v229, v229, 0, vcc
	v_cndmask_b32_e64 v228, v228, 0, vcc
	v_pk_fma_f32 v[230:231], v[72:73], v[230:231], v[76:77]
	v_cndmask_b32_e64 v221, v219, 0, s[52:53]
	v_cndmask_b32_e64 v220, v198, 0, s[52:53]
	v_pk_fma_f32 v[228:229], v[74:75], v[228:229], v[78:79]
	v_pk_fma_f32 v[160:161], v[68:69], v[160:161], v[230:231]
	v_pk_fma_f32 v[220:221], v[70:71], v[220:221], v[228:229]
	v_pk_fma_f32 v[156:157], v[156:157], v[60:61], v[160:161]
	v_pk_fma_f32 v[158:159], v[158:159], v[62:63], v[220:221]
	v_pk_mul_f32 v[220:221], v[156:157], v[156:157]
	v_mov_b64_e32 v[228:229], s[70:71]
	v_pk_fma_f32 v[220:221], v[220:221], s[68:69], v[228:229] op_sel_hi:[1,0,0] neg_lo:[1,0,0] neg_hi:[1,0,0]
	v_pk_add_f32 v[148:149], v[148:149], v[56:57]
	v_pk_mul_f32 v[220:221], v[156:157], v[220:221]
	v_pk_mul_f32 v[160:161], v[158:159], v[158:159]
	v_exp_f32_e32 v220, v220
	v_exp_f32_e32 v221, v221
	v_pk_add_f32 v[150:151], v[150:151], v[58:59]
	v_cndmask_b32_e64 v198, v239, v165, s[44:45]
	v_cndmask_b32_e64 v219, v241, v167, s[44:45]
	v_pk_add_f32 v[220:221], v[220:221], 1.0 op_sel_hi:[1,0]
	v_pk_add_f32 v[144:145], v[144:145], v[80:81]
	v_rcp_f32_e32 v220, v220
	v_rcp_f32_e32 v221, v221
	v_pk_add_f32 v[146:147], v[146:147], v[82:83]
	v_pk_add_f32 v[142:143], v[142:143], v[94:95]
	v_pk_add_f32 v[140:141], v[140:141], v[92:93]
	v_pk_mul_f32 v[156:157], v[156:157], v[220:221]
	v_cndmask_b32_e64 v221, v219, 0, vcc
	v_pk_mul_f32 v[148:149], v[148:149], v[156:157]
	v_pk_fma_f32 v[156:157], v[160:161], s[68:69], v[228:229] op_sel_hi:[1,0,0] neg_lo:[1,0,0] neg_hi:[1,0,0]
	v_cndmask_b32_e64 v160, v242, v168, s[44:45]
	v_pk_mul_f32 v[156:157], v[158:159], v[156:157]
	v_cndmask_b32_e64 v161, v243, v169, s[44:45]
	v_exp_f32_e32 v156, v156
	v_exp_f32_e32 v157, v157
	v_cndmask_b32_e64 v220, v198, 0, vcc
	v_cndmask_b32_e64 v161, v161, 0, vcc
	v_cndmask_b32_e64 v160, v160, 0, vcc
	v_pk_add_f32 v[156:157], v[156:157], 1.0 op_sel_hi:[1,0]
	v_pk_fma_f32 v[220:221], v[48:49], v[220:221], v[52:53]
	v_rcp_f32_e32 v156, v156
	v_rcp_f32_e32 v157, v157
	v_pk_fma_f32 v[160:161], v[50:51], v[160:161], v[54:55]
	v_pk_mul_f32 v[156:157], v[158:159], v[156:157]
	s_nop 0
	v_pk_mul_f32 v[150:151], v[150:151], v[156:157]
	v_cndmask_b32_e64 v156, v162, v236, s[42:43]
	v_cndmask_b32_e64 v157, v163, v237, s[42:43]
	v_cndmask_b32_e64 v158, v164, v238, s[42:43]
	v_cndmask_b32_e64 v159, v166, v240, s[42:43]
	v_cndmask_b32_e64 v157, v157, 0, s[52:53]
	v_cndmask_b32_e64 v156, v156, 0, s[52:53]
	v_cndmask_b32_e64 v159, v159, 0, s[52:53]
	v_cndmask_b32_e64 v158, v158, 0, s[52:53]
	v_pk_fma_f32 v[156:157], v[44:45], v[156:157], v[220:221]
	v_pk_fma_f32 v[158:159], v[46:47], v[158:159], v[160:161]
	v_pk_fma_f32 v[152:153], v[152:153], v[40:41], v[156:157]
	v_pk_fma_f32 v[154:155], v[154:155], v[42:43], v[158:159]
	v_pk_mul_f32 v[158:159], v[152:153], v[152:153]
	v_pk_mul_f32 v[156:157], v[154:155], v[154:155]
	v_pk_fma_f32 v[158:159], v[158:159], s[68:69], v[228:229] op_sel_hi:[1,0,0] neg_lo:[1,0,0] neg_hi:[1,0,0]
	s_nop 0
	v_pk_mul_f32 v[158:159], v[152:153], v[158:159]
	s_nop 0
	v_exp_f32_e32 v158, v158
	v_exp_f32_e32 v159, v159
	v_mov_b32_dpp v160, v142 row_ror:2 row_mask:0xf bank_mask:0xf
	v_mov_b32_dpp v161, v143 row_ror:2 row_mask:0xf bank_mask:0xf
	v_pk_add_f32 v[158:159], v[158:159], 1.0 op_sel_hi:[1,0]
	s_nop 0
	v_rcp_f32_e32 v158, v158
	v_rcp_f32_e32 v159, v159
	s_nop 0
	v_pk_mul_f32 v[152:153], v[152:153], v[158:159]
	s_nop 0
	v_pk_mul_f32 v[152:153], v[144:145], v[152:153]
	v_pk_fma_f32 v[144:145], v[156:157], s[68:69], v[228:229] op_sel_hi:[1,0,0] neg_lo:[1,0,0] neg_hi:[1,0,0]
	s_nop 0
	v_pk_mul_f32 v[144:145], v[154:155], v[144:145]
	s_nop 0
	v_exp_f32_e32 v144, v144
	v_exp_f32_e32 v145, v145
	s_nop 1
	v_mov_b32_dpp v156, v142 row_ror:1 row_mask:0xf bank_mask:0xf
	v_pk_add_f32 v[144:145], v[144:145], 1.0 op_sel_hi:[1,0]
	v_mov_b32_dpp v158, v143 row_ror:1 row_mask:0xf bank_mask:0xf
	v_rcp_f32_e32 v144, v144
	v_rcp_f32_e32 v145, v145
	v_mov_b32_dpp v157, v140 row_ror:2 row_mask:0xf bank_mask:0xf
	v_mov_b32_dpp v159, v141 row_ror:2 row_mask:0xf bank_mask:0xf
	v_pk_mul_f32 v[144:145], v[154:155], v[144:145]
	s_nop 0
	v_pk_mul_f32 v[154:155], v[146:147], v[144:145]
	v_cvt_pk_bf16_f32 v144, v148, v149
	v_mov_b64_e32 v[148:149], s[86:87]
	v_mad_i64_i32 v[148:149], s[0:1], v218, s40, v[148:149]
	v_lshl_add_u64 v[148:149], v[210:211], 1, v[148:149]
	v_or_b32_e32 v218, 32, v227
	v_cvt_pk_bf16_f32 v145, v150, v151
	v_cvt_pk_bf16_f32 v146, v152, v153
	v_cvt_pk_bf16_f32 v147, v154, v155
	global_store_dwordx4 v[148:149], v[144:147], off
	s_nop 1
	v_mul_hi_i32 v144, v218, s14
	v_lshrrev_b32_e32 v145, 31, v144
	v_ashrrev_i32_e32 v144, 7, v144
	v_add_u32_e32 v144, v144, v145
	v_mad_i32_i24 v219, v144, s15, v218
	v_ashrrev_i32_e32 v145, 31, v144
	v_add_u32_e32 v198, 0xfffff7f2, v219
	v_lshl_add_u64 v[144:145], v[144:145], 1, v[198:199]
	v_mad_u64_u32 v[146:147], s[0:1], v144, s39, 0
	v_mad_i32_i24 v147, v145, s39, v147
	v_lshl_add_u64 v[144:145], s[62:63], 0, v[146:147]
	v_cmp_lt_i32_e32 vcc, s38, v219
	v_mov_b32_dpp v154, v140 row_ror:1 row_mask:0xf bank_mask:0xf
	v_mov_b32_dpp v155, v141 row_ror:1 row_mask:0xf bank_mask:0xf
	v_lshl_add_u64 v[144:145], v[210:211], 2, v[144:145]
	s_and_saveexec_b64 s[0:1], vcc
	s_cbranch_execz .LBB0_948
	global_store_dwordx4 v[144:145], v[140:143], off
.LBB0_948:
	s_or_b64 exec, exec, s[0:1]
	v_pk_add_f32 v[138:139], v[138:139], v[90:91]
	v_pk_add_f32 v[136:137], v[136:137], v[88:89]
	s_nop 7
	v_mov_b32_dpp v146, v136 row_ror:1 row_mask:0xf bank_mask:0xf
	v_mov_b32_dpp v147, v137 row_ror:1 row_mask:0xf bank_mask:0xf
	v_mov_b32_dpp v148, v138 row_ror:1 row_mask:0xf bank_mask:0xf
	v_mov_b32_dpp v150, v139 row_ror:1 row_mask:0xf bank_mask:0xf
	v_mov_b32_dpp v149, v136 row_ror:2 row_mask:0xf bank_mask:0xf
	v_mov_b32_dpp v151, v137 row_ror:2 row_mask:0xf bank_mask:0xf
	v_mov_b32_dpp v152, v138 row_ror:2 row_mask:0xf bank_mask:0xf
	v_mov_b32_dpp v153, v139 row_ror:2 row_mask:0xf bank_mask:0xf
	s_and_saveexec_b64 s[0:1], vcc
	s_cbranch_execz .LBB0_950
	global_store_dwordx4 v[144:145], v[136:139], off offset:16
.LBB0_950:
	s_or_b64 exec, exec, s[0:1]
	v_cmp_eq_u32_e64 s[52:53], 0, v219
	v_cmp_gt_i32_e32 vcc, 2, v219
	v_cndmask_b32_e64 v174, v158, v174, s[42:43]
	v_cndmask_b32_e64 v198, v173, v157, s[44:45]
	v_cndmask_b32_e64 v175, v175, v159, s[44:45]
	v_cndmask_b32_e64 v172, v156, v172, s[42:43]
	v_cndmask_b32_e64 v144, v154, v170, s[42:43]
	v_cndmask_b32_e64 v145, v155, v171, s[42:43]
	v_cndmask_b32_e64 v216, v216, v160, s[44:45]
	v_cndmask_b32_e64 v173, v217, v161, s[44:45]
	v_cndmask_b32_e64 v171, v174, 0, s[52:53]
	v_cndmask_b32_e64 v175, v175, 0, vcc
	v_cndmask_b32_e64 v174, v198, 0, vcc
	v_cndmask_b32_e64 v145, v145, 0, s[52:53]
	v_cndmask_b32_e64 v144, v144, 0, s[52:53]
	v_cndmask_b32_e64 v170, v172, 0, s[52:53]
	v_cndmask_b32_e64 v173, v173, 0, vcc
	v_cndmask_b32_e64 v172, v216, 0, vcc
	v_pk_fma_f32 v[174:175], v[72:73], v[174:175], v[76:77]
	v_pk_fma_f32 v[172:173], v[74:75], v[172:173], v[78:79]
	v_pk_fma_f32 v[144:145], v[68:69], v[144:145], v[174:175]
	v_pk_fma_f32 v[170:171], v[70:71], v[170:171], v[172:173]
	v_pk_fma_f32 v[140:141], v[140:141], v[60:61], v[144:145]
	v_pk_fma_f32 v[142:143], v[142:143], v[62:63], v[170:171]
	v_pk_mul_f32 v[170:171], v[140:141], v[140:141]
	v_mov_b64_e32 v[172:173], s[70:71]
	v_pk_fma_f32 v[170:171], v[170:171], s[68:69], v[172:173] op_sel_hi:[1,0,0] neg_lo:[1,0,0] neg_hi:[1,0,0]
	v_pk_add_f32 v[132:133], v[132:133], v[56:57]
	v_pk_mul_f32 v[170:171], v[140:141], v[170:171]
	v_pk_mul_f32 v[144:145], v[142:143], v[142:143]
	v_exp_f32_e32 v170, v170
	v_exp_f32_e32 v171, v171
	v_pk_add_f32 v[134:135], v[134:135], v[58:59]
	v_pk_add_f32 v[128:129], v[128:129], v[80:81]
	v_pk_add_f32 v[130:131], v[130:131], v[82:83]
	v_pk_add_f32 v[170:171], v[170:171], 1.0 op_sel_hi:[1,0]
	v_pk_add_f32 v[126:127], v[126:127], v[94:95]
	v_rcp_f32_e32 v170, v170
	v_rcp_f32_e32 v171, v171
	v_pk_add_f32 v[124:125], v[124:125], v[92:93]
	v_pk_mul_f32 v[140:141], v[140:141], v[170:171]
	s_nop 0
	v_pk_mul_f32 v[132:133], v[132:133], v[140:141]
	v_pk_fma_f32 v[140:141], v[144:145], s[68:69], v[172:173] op_sel_hi:[1,0,0] neg_lo:[1,0,0] neg_hi:[1,0,0]
	v_cndmask_b32_e64 v144, v168, v152, s[44:45]
	v_pk_mul_f32 v[140:141], v[142:143], v[140:141]
	v_cndmask_b32_e64 v145, v169, v153, s[44:45]
	v_exp_f32_e32 v140, v140
	v_exp_f32_e32 v141, v141
	v_cndmask_b32_e64 v145, v145, 0, vcc
	v_cndmask_b32_e64 v144, v144, 0, vcc
	v_pk_fma_f32 v[144:145], v[50:51], v[144:145], v[54:55]
	v_pk_add_f32 v[140:141], v[140:141], 1.0 op_sel_hi:[1,0]
	s_nop 0
	v_rcp_f32_e32 v140, v140
	v_rcp_f32_e32 v141, v141
	s_nop 0
	v_pk_mul_f32 v[140:141], v[142:143], v[140:141]
	s_nop 0
	v_pk_mul_f32 v[134:135], v[134:135], v[140:141]
	v_cndmask_b32_e64 v140, v146, v162, s[42:43]
	v_cndmask_b32_e64 v141, v147, v163, s[42:43]
	v_cndmask_b32_e64 v162, v165, v149, s[44:45]
	v_cndmask_b32_e64 v163, v167, v151, s[44:45]
	v_cndmask_b32_e64 v163, v163, 0, vcc
	v_cndmask_b32_e64 v162, v162, 0, vcc
	v_cndmask_b32_e64 v142, v148, v164, s[42:43]
	v_cndmask_b32_e64 v143, v150, v166, s[42:43]
	v_cndmask_b32_e64 v141, v141, 0, s[52:53]
	v_cndmask_b32_e64 v140, v140, 0, s[52:53]
	v_pk_fma_f32 v[162:163], v[48:49], v[162:163], v[52:53]
	v_cndmask_b32_e64 v143, v143, 0, s[52:53]
	v_cndmask_b32_e64 v142, v142, 0, s[52:53]
	v_pk_fma_f32 v[140:141], v[44:45], v[140:141], v[162:163]
	v_pk_fma_f32 v[142:143], v[46:47], v[142:143], v[144:145]
	v_pk_fma_f32 v[136:137], v[136:137], v[40:41], v[140:141]
	v_pk_fma_f32 v[138:139], v[138:139], v[42:43], v[142:143]
	v_pk_mul_f32 v[142:143], v[136:137], v[136:137]
	v_pk_mul_f32 v[140:141], v[138:139], v[138:139]
	v_pk_fma_f32 v[142:143], v[142:143], s[68:69], v[172:173] op_sel_hi:[1,0,0] neg_lo:[1,0,0] neg_hi:[1,0,0]
	s_nop 0
	v_pk_mul_f32 v[142:143], v[136:137], v[142:143]
	s_nop 0
	v_exp_f32_e32 v142, v142
	v_exp_f32_e32 v143, v143
	s_nop 1
	v_mov_b32_dpp v144, v127 row_ror:1 row_mask:0xf bank_mask:0xf
	v_pk_add_f32 v[142:143], v[142:143], 1.0 op_sel_hi:[1,0]
	v_mov_b32_dpp v145, v125 row_ror:2 row_mask:0xf bank_mask:0xf
	v_rcp_f32_e32 v142, v142
	v_rcp_f32_e32 v143, v143
	v_mov_b32_dpp v162, v126 row_ror:2 row_mask:0xf bank_mask:0xf
	v_mov_b32_dpp v163, v127 row_ror:2 row_mask:0xf bank_mask:0xf
	v_pk_mul_f32 v[136:137], v[136:137], v[142:143]
	s_nop 0
	v_pk_mul_f32 v[136:137], v[128:129], v[136:137]
	v_pk_fma_f32 v[128:129], v[140:141], s[68:69], v[172:173] op_sel_hi:[1,0,0] neg_lo:[1,0,0] neg_hi:[1,0,0]
	s_nop 0
	v_pk_mul_f32 v[128:129], v[138:139], v[128:129]
	s_nop 0
	v_exp_f32_e32 v128, v128
	v_exp_f32_e32 v129, v129
	s_nop 1
	v_mov_b32_dpp v140, v124 row_ror:1 row_mask:0xf bank_mask:0xf
	v_pk_add_f32 v[128:129], v[128:129], 1.0 op_sel_hi:[1,0]
	v_mov_b32_dpp v141, v125 row_ror:1 row_mask:0xf bank_mask:0xf
	v_rcp_f32_e32 v128, v128
	v_rcp_f32_e32 v129, v129
	v_mov_b32_dpp v142, v126 row_ror:1 row_mask:0xf bank_mask:0xf
	v_mov_b32_dpp v143, v124 row_ror:2 row_mask:0xf bank_mask:0xf
	v_pk_mul_f32 v[128:129], v[138:139], v[128:129]
	s_nop 0
	v_pk_mul_f32 v[138:139], v[130:131], v[128:129]
	v_cvt_pk_bf16_f32 v128, v132, v133
	v_mov_b64_e32 v[132:133], s[86:87]
	v_mad_i64_i32 v[132:133], s[0:1], v218, s40, v[132:133]
	v_cvt_pk_bf16_f32 v129, v134, v135
	v_cvt_pk_bf16_f32 v130, v136, v137
	v_lshl_add_u64 v[132:133], v[210:211], 1, v[132:133]
	v_cvt_pk_bf16_f32 v131, v138, v139
	global_store_dwordx4 v[132:133], v[128:131], off
	s_nop 1
	v_or_b32_e32 v130, 48, v227
	v_mul_hi_i32 v128, v130, s14
	v_lshrrev_b32_e32 v129, 31, v128
	v_ashrrev_i32_e32 v128, 7, v128
	v_add_u32_e32 v128, v128, v129
	v_mad_i32_i24 v139, v128, s15, v130
	v_ashrrev_i32_e32 v129, 31, v128
	v_add_u32_e32 v198, 0xfffff7f2, v139
	v_lshl_add_u64 v[128:129], v[128:129], 1, v[198:199]
	v_mad_u64_u32 v[132:133], s[4:5], v128, s39, 0
	v_mad_i32_i24 v133, v129, s39, v133
	v_lshl_add_u64 v[128:129], s[62:63], 0, v[132:133]
	v_cmp_lt_i32_e64 s[0:1], s38, v139
	v_lshl_add_u64 v[128:129], v[210:211], 2, v[128:129]
	s_and_saveexec_b64 s[34:35], s[0:1]
	s_cbranch_execz .LBB0_952
	global_store_dwordx4 v[128:129], v[124:127], off

.LBB0_954:
	s_or_b64 exec, exec, s[34:35]
	v_pk_add_f32 v[122:123], v[122:123], v[90:91]
	v_pk_add_f32 v[120:121], v[120:121], v[88:89]
	s_nop 7
	v_mov_b32_dpp v131, v120 row_ror:1 row_mask:0xf bank_mask:0xf
	v_mov_b32_dpp v132, v121 row_ror:1 row_mask:0xf bank_mask:0xf
	v_mov_b32_dpp v133, v122 row_ror:1 row_mask:0xf bank_mask:0xf
	v_mov_b32_dpp v135, v123 row_ror:1 row_mask:0xf bank_mask:0xf
	v_mov_b32_dpp v134, v120 row_ror:2 row_mask:0xf bank_mask:0xf
	v_mov_b32_dpp v136, v121 row_ror:2 row_mask:0xf bank_mask:0xf
	v_mov_b32_dpp v137, v122 row_ror:2 row_mask:0xf bank_mask:0xf
	v_mov_b32_dpp v138, v123 row_ror:2 row_mask:0xf bank_mask:0xf
	s_and_saveexec_b64 s[34:35], s[0:1]
	s_cbranch_execz .LBB0_956
	global_store_dwordx4 v[128:129], v[120:123], off offset:16

.LBB0_958:
	s_or_b64 exec, exec, s[0:1]
	v_cmp_gt_i32_e32 vcc, 2, v139
	v_cndmask_b32_e64 v140, v140, v154, s[42:43]
	v_cndmask_b32_e64 v141, v141, v155, s[42:43]
	v_cndmask_b32_e64 v154, v157, v143, s[44:45]
	v_cndmask_b32_e64 v155, v159, v145, s[44:45]
	v_cmp_eq_u32_e64 s[52:53], 0, v139
	v_cndmask_b32_e64 v139, v142, v156, s[42:43]
	v_cndmask_b32_e64 v142, v144, v158, s[42:43]
	v_cndmask_b32_e64 v144, v160, v162, s[44:45]
	v_cndmask_b32_e64 v145, v161, v163, s[44:45]
	v_cndmask_b32_e64 v155, v155, 0, vcc
	v_cndmask_b32_e64 v154, v154, 0, vcc
	v_cndmask_b32_e64 v141, v141, 0, s[52:53]
	v_cndmask_b32_e64 v140, v140, 0, s[52:53]
	v_cndmask_b32_e64 v145, v145, 0, vcc
	v_cndmask_b32_e64 v144, v144, 0, vcc
	v_pk_fma_f32 v[154:155], v[72:73], v[154:155], v[76:77]
	v_cndmask_b32_e64 v143, v142, 0, s[52:53]
	v_cndmask_b32_e64 v142, v139, 0, s[52:53]
	v_pk_fma_f32 v[144:145], v[74:75], v[144:145], v[78:79]
	v_pk_fma_f32 v[140:141], v[68:69], v[140:141], v[154:155]
	v_pk_fma_f32 v[142:143], v[70:71], v[142:143], v[144:145]
	v_pk_fma_f32 v[124:125], v[124:125], v[60:61], v[140:141]
	v_pk_fma_f32 v[126:127], v[126:127], v[62:63], v[142:143]
	v_pk_mul_f32 v[142:143], v[124:125], v[124:125]
	v_mov_b64_e32 v[144:145], s[70:71]
	v_pk_fma_f32 v[142:143], v[142:143], s[68:69], v[144:145] op_sel_hi:[1,0,0] neg_lo:[1,0,0] neg_hi:[1,0,0]
	v_pk_add_f32 v[116:117], v[116:117], v[56:57]
	v_pk_mul_f32 v[142:143], v[124:125], v[142:143]
	v_pk_mul_f32 v[140:141], v[126:127], v[126:127]
	v_exp_f32_e32 v142, v142
	v_exp_f32_e32 v143, v143
	v_pk_add_f32 v[118:119], v[118:119], v[58:59]
	v_pk_add_f32 v[112:113], v[112:113], v[80:81]
	v_pk_add_f32 v[114:115], v[114:115], v[82:83]
	v_pk_add_f32 v[142:143], v[142:143], 1.0 op_sel_hi:[1,0]
	v_pk_add_f32 v[110:111], v[110:111], v[94:95]
	v_rcp_f32_e32 v142, v142
	v_rcp_f32_e32 v143, v143
	v_pk_add_f32 v[108:109], v[108:109], v[92:93]
	v_pk_mul_f32 v[124:125], v[124:125], v[142:143]
	s_nop 0
	v_pk_mul_f32 v[116:117], v[116:117], v[124:125]
	v_pk_fma_f32 v[124:125], v[140:141], s[68:69], v[144:145] op_sel_hi:[1,0,0] neg_lo:[1,0,0] neg_hi:[1,0,0]
	s_nop 0
	v_pk_mul_f32 v[124:125], v[126:127], v[124:125]
	s_nop 0
	v_exp_f32_e32 v124, v124
	v_exp_f32_e32 v125, v125
	s_nop 0
	v_pk_add_f32 v[124:125], v[124:125], 1.0 op_sel_hi:[1,0]
	s_nop 0
	v_rcp_f32_e32 v124, v124
	v_rcp_f32_e32 v125, v125
	s_nop 0
	v_pk_mul_f32 v[124:125], v[126:127], v[124:125]
	s_nop 0
	v_pk_mul_f32 v[118:119], v[118:119], v[124:125]
	v_cndmask_b32_e64 v124, v131, v146, s[42:43]
	v_cndmask_b32_e64 v131, v149, v134, s[44:45]
	v_cndmask_b32_e64 v134, v151, v136, s[44:45]
	v_cndmask_b32_e64 v126, v133, v148, s[42:43]
	v_cndmask_b32_e64 v127, v135, v150, s[42:43]
	v_cndmask_b32_e64 v125, v132, v147, s[42:43]
	v_cndmask_b32_e64 v132, v152, v137, s[44:45]
	v_cndmask_b32_e64 v133, v153, v138, s[44:45]
	v_cndmask_b32_e64 v135, v134, 0, vcc
	v_cndmask_b32_e64 v134, v131, 0, vcc
	v_cndmask_b32_e64 v125, v125, 0, s[52:53]
	v_cndmask_b32_e64 v124, v124, 0, s[52:53]
	v_cndmask_b32_e64 v133, v133, 0, vcc
	v_cndmask_b32_e64 v132, v132, 0, vcc
	v_pk_fma_f32 v[134:135], v[48:49], v[134:135], v[52:53]
	v_cndmask_b32_e64 v127, v127, 0, s[52:53]
	v_cndmask_b32_e64 v126, v126, 0, s[52:53]
	v_pk_fma_f32 v[132:133], v[50:51], v[132:133], v[54:55]
	v_pk_fma_f32 v[124:125], v[44:45], v[124:125], v[134:135]
	v_pk_fma_f32 v[126:127], v[46:47], v[126:127], v[132:133]
	v_pk_fma_f32 v[120:121], v[120:121], v[40:41], v[124:125]
	v_pk_fma_f32 v[122:123], v[122:123], v[42:43], v[126:127]
	v_pk_mul_f32 v[126:127], v[120:121], v[120:121]
	v_pk_mul_f32 v[124:125], v[122:123], v[122:123]
	v_pk_fma_f32 v[126:127], v[126:127], s[68:69], v[144:145] op_sel_hi:[1,0,0] neg_lo:[1,0,0] neg_hi:[1,0,0]
	s_nop 0
	v_pk_mul_f32 v[126:127], v[120:121], v[126:127]
	s_nop 0
	v_exp_f32_e32 v126, v126
	v_exp_f32_e32 v127, v127
	s_nop 2
	v_pk_add_f32 v[126:127], v[126:127], 1.0 op_sel_hi:[1,0]
	s_nop 0
	v_rcp_f32_e32 v126, v126
	v_rcp_f32_e32 v127, v127
	s_nop 1
	v_mov_b32_dpp v131, v108 row_ror:1 row_mask:0xf bank_mask:0xf
	v_pk_mul_f32 v[120:121], v[120:121], v[126:127]
	v_mov_b32_dpp v132, v109 row_ror:1 row_mask:0xf bank_mask:0xf
	v_pk_mul_f32 v[120:121], v[112:113], v[120:121]
	v_pk_fma_f32 v[112:113], v[124:125], s[68:69], v[144:145] op_sel_hi:[1,0,0] neg_lo:[1,0,0] neg_hi:[1,0,0]
	v_mov_b32_dpp v133, v110 row_ror:1 row_mask:0xf bank_mask:0xf
	v_pk_mul_f32 v[112:113], v[122:123], v[112:113]
	v_mov_b32_dpp v135, v111 row_ror:1 row_mask:0xf bank_mask:0xf
	v_exp_f32_e32 v112, v112
	v_exp_f32_e32 v113, v113
	v_mov_b32_dpp v134, v108 row_ror:2 row_mask:0xf bank_mask:0xf
	v_mov_b32_dpp v136, v109 row_ror:2 row_mask:0xf bank_mask:0xf
	v_mov_b32_dpp v137, v110 row_ror:2 row_mask:0xf bank_mask:0xf
	v_pk_add_f32 v[112:113], v[112:113], 1.0 op_sel_hi:[1,0]
	v_mov_b32_dpp v138, v111 row_ror:2 row_mask:0xf bank_mask:0xf
	v_rcp_f32_e32 v112, v112
	v_rcp_f32_e32 v113, v113
	s_nop 0
	v_pk_mul_f32 v[112:113], v[122:123], v[112:113]
	s_nop 0
	v_pk_mul_f32 v[122:123], v[114:115], v[112:113]
	v_cvt_pk_bf16_f32 v112, v116, v117
	v_mov_b64_e32 v[116:117], s[86:87]
	v_mad_i64_i32 v[116:117], s[0:1], v130, s40, v[116:117]
	s_add_i32 s0, s30, 2
	v_cvt_pk_bf16_f32 v113, v118, v119
	v_cvt_pk_bf16_f32 v114, v120, v121
	v_lshl_add_u64 v[116:117], v[210:211], 1, v[116:117]
	v_lshl_or_b32 v120, s0, 6, v200
	v_cvt_pk_bf16_f32 v115, v122, v123
	global_store_dwordx4 v[116:117], v[112:115], off
	s_nop 1
	v_mul_hi_i32 v112, v120, s14
	v_lshrrev_b32_e32 v113, 31, v112
	v_ashrrev_i32_e32 v112, 7, v112
	v_add_u32_e32 v112, v112, v113
	v_mad_i32_i24 v139, v112, s15, v120
	v_ashrrev_i32_e32 v113, 31, v112
	v_add_u32_e32 v198, 0xfffff7f2, v139
	v_lshl_add_u64 v[112:113], v[112:113], 1, v[198:199]
	v_mad_u64_u32 v[114:115], s[4:5], v112, s39, 0
	v_mad_i32_i24 v115, v113, s39, v115
	v_lshl_add_u64 v[112:113], s[62:63], 0, v[114:115]
	v_cmp_lt_i32_e32 vcc, s38, v139
	v_lshl_add_u64 v[114:115], v[210:211], 2, v[112:113]
	s_and_saveexec_b64 s[30:31], vcc
	s_cbranch_execz .LBB0_960
	global_store_dwordx4 v[114:115], v[108:111], off

.LBB0_962:
	s_or_b64 exec, exec, s[0:1]
	v_pk_add_f32 v[106:107], v[106:107], v[90:91]
	v_pk_add_f32 v[104:105], v[104:105], v[88:89]
	s_nop 7
	v_mov_b32_dpp v121, v104 row_ror:1 row_mask:0xf bank_mask:0xf
	v_mov_b32_dpp v122, v105 row_ror:1 row_mask:0xf bank_mask:0xf
	v_mov_b32_dpp v123, v106 row_ror:1 row_mask:0xf bank_mask:0xf
	v_mov_b32_dpp v125, v107 row_ror:1 row_mask:0xf bank_mask:0xf
	v_mov_b32_dpp v124, v104 row_ror:2 row_mask:0xf bank_mask:0xf
	v_mov_b32_dpp v126, v105 row_ror:2 row_mask:0xf bank_mask:0xf
	v_mov_b32_dpp v127, v106 row_ror:2 row_mask:0xf bank_mask:0xf
	v_mov_b32_dpp v130, v107 row_ror:2 row_mask:0xf bank_mask:0xf
	s_and_saveexec_b64 s[0:1], vcc
	s_cbranch_execz .LBB0_964
	global_store_dwordx4 v[114:115], v[104:107], off offset:16

.LBB0_966:
	s_or_b64 exec, exec, s[0:1]
	v_cmp_eq_u32_e32 vcc, 0, v139
	v_cndmask_b32_e64 v140, 0, v134, s[44:45]
	v_cndmask_b32_e64 v141, 0, v136, s[44:45]
	s_or_b64 s[0:1], s[42:43], vcc
	v_cmp_gt_i32_e32 vcc, 2, v139
	v_cndmask_b32_e64 v118, 0, v137, s[44:45]
	v_cndmask_b32_e64 v119, 0, v138, s[44:45]
	v_cndmask_b32_e64 v141, v141, 0, vcc
	v_cndmask_b32_e64 v140, v140, 0, vcc
	v_cndmask_b32_e64 v115, v132, 0, s[0:1]
	v_cndmask_b32_e64 v114, v131, 0, s[0:1]
	v_cndmask_b32_e64 v119, v119, 0, vcc
	v_cndmask_b32_e64 v118, v118, 0, vcc
	v_pk_fma_f32 v[140:141], v[72:73], v[140:141], v[76:77]
	v_cndmask_b32_e64 v117, v135, 0, s[0:1]
	v_cndmask_b32_e64 v116, v133, 0, s[0:1]
	v_pk_fma_f32 v[118:119], v[74:75], v[118:119], v[78:79]
	v_pk_fma_f32 v[114:115], v[68:69], v[114:115], v[140:141]
	v_pk_fma_f32 v[116:117], v[70:71], v[116:117], v[118:119]
	v_pk_fma_f32 v[108:109], v[108:109], v[60:61], v[114:115]
	v_pk_fma_f32 v[110:111], v[110:111], v[62:63], v[116:117]
	v_pk_mul_f32 v[116:117], v[108:109], v[108:109]
	v_mov_b64_e32 v[118:119], s[70:71]
	v_pk_mul_f32 v[114:115], v[110:111], v[110:111]
	v_pk_fma_f32 v[116:117], v[116:117], s[68:69], v[118:119] op_sel_hi:[1,0,0] neg_lo:[1,0,0] neg_hi:[1,0,0]
	v_pk_fma_f32 v[114:115], v[114:115], s[68:69], v[118:119] op_sel_hi:[1,0,0] neg_lo:[1,0,0] neg_hi:[1,0,0]
	v_pk_mul_f32 v[116:117], v[108:109], v[116:117]
	v_pk_mul_f32 v[114:115], v[110:111], v[114:115]
	v_exp_f32_e32 v116, v116
	v_exp_f32_e32 v117, v117
	v_exp_f32_e32 v114, v114
	v_exp_f32_e32 v115, v115
	v_cndmask_b32_e64 v139, 0, v124, s[44:45]
	v_pk_add_f32 v[116:117], v[116:117], 1.0 op_sel_hi:[1,0]
	v_cndmask_b32_e64 v140, 0, v126, s[44:45]
	v_rcp_f32_e32 v116, v116
	v_rcp_f32_e32 v117, v117
	v_pk_add_f32 v[114:115], v[114:115], 1.0 op_sel_hi:[1,0]
	v_cndmask_b32_e64 v141, v140, 0, vcc
	v_rcp_f32_e32 v114, v114
	v_rcp_f32_e32 v115, v115
	v_pk_mul_f32 v[108:109], v[108:109], v[116:117]
	v_cndmask_b32_e64 v116, 0, v127, s[44:45]
	v_cndmask_b32_e64 v117, 0, v130, s[44:45]
	v_cndmask_b32_e64 v140, v139, 0, vcc
	v_pk_mul_f32 v[100:101], v[100:101], v[108:109]
	v_pk_mul_f32 v[108:109], v[110:111], v[114:115]
	v_cndmask_b32_e64 v111, v122, 0, s[0:1]
	v_cndmask_b32_e64 v110, v121, 0, s[0:1]
	v_cndmask_b32_e64 v117, v117, 0, vcc
	v_cndmask_b32_e64 v116, v116, 0, vcc
	v_pk_fma_f32 v[140:141], v[48:49], v[140:141], v[52:53]
	v_cndmask_b32_e64 v115, v125, 0, s[0:1]
	v_cndmask_b32_e64 v114, v123, 0, s[0:1]
	v_pk_fma_f32 v[116:117], v[50:51], v[116:117], v[54:55]
	v_pk_fma_f32 v[110:111], v[44:45], v[110:111], v[140:141]
	v_pk_fma_f32 v[114:115], v[46:47], v[114:115], v[116:117]
	v_pk_fma_f32 v[104:105], v[104:105], v[40:41], v[110:111]
	v_pk_fma_f32 v[106:107], v[106:107], v[42:43], v[114:115]
	v_pk_mul_f32 v[114:115], v[104:105], v[104:105]
	v_pk_mul_f32 v[110:111], v[106:107], v[106:107]
	v_pk_fma_f32 v[114:115], v[114:115], s[68:69], v[118:119] op_sel_hi:[1,0,0] neg_lo:[1,0,0] neg_hi:[1,0,0]
	v_pk_fma_f32 v[110:111], v[110:111], s[68:69], v[118:119] op_sel_hi:[1,0,0] neg_lo:[1,0,0] neg_hi:[1,0,0]
	v_pk_mul_f32 v[114:115], v[104:105], v[114:115]
	v_pk_mul_f32 v[110:111], v[106:107], v[110:111]
	v_exp_f32_e32 v114, v114
	v_exp_f32_e32 v115, v115
	v_exp_f32_e32 v110, v110
	v_exp_f32_e32 v111, v111
	v_or_b32_e32 v116, 16, v120
	v_pk_add_f32 v[114:115], v[114:115], 1.0 op_sel_hi:[1,0]
	v_pk_mul_f32 v[102:103], v[102:103], v[108:109]
	v_rcp_f32_e32 v114, v114
	v_rcp_f32_e32 v115, v115
	v_pk_add_f32 v[110:111], v[110:111], 1.0 op_sel_hi:[1,0]
	v_pk_add_f32 v[86:87], v[86:87], v[94:95]
	v_rcp_f32_e32 v110, v110
	v_rcp_f32_e32 v111, v111
	v_pk_mul_f32 v[104:105], v[104:105], v[114:115]
	v_pk_add_f32 v[84:85], v[84:85], v[92:93]
	v_pk_mul_f32 v[104:105], v[96:97], v[104:105]
	v_pk_mul_f32 v[96:97], v[106:107], v[110:111]
	s_nop 0
	v_pk_mul_f32 v[106:107], v[98:99], v[96:97]
	v_cvt_pk_bf16_f32 v96, v100, v101
	v_mov_b64_e32 v[100:101], s[86:87]
	v_mad_i64_i32 v[100:101], s[0:1], v120, s40, v[100:101]
	v_lshl_add_u64 v[100:101], v[210:211], 1, v[100:101]
	v_cvt_pk_bf16_f32 v97, v102, v103
	v_cvt_pk_bf16_f32 v98, v104, v105
	v_cvt_pk_bf16_f32 v99, v106, v107
	global_store_dwordx4 v[100:101], v[96:99], off
	s_nop 1
	v_mul_hi_i32 v96, v116, s14
	v_lshrrev_b32_e32 v97, 31, v96
	v_ashrrev_i32_e32 v96, 7, v96
	v_add_u32_e32 v96, v96, v97
	v_mad_i32_i24 v117, v96, s15, v116
	v_ashrrev_i32_e32 v97, 31, v96
	v_add_u32_e32 v198, 0xfffff7f2, v117
	v_lshl_add_u64 v[96:97], v[96:97], 1, v[198:199]
	v_mad_u64_u32 v[98:99], s[0:1], v96, s39, 0
	v_mad_i32_i24 v99, v97, s39, v99
	s_nop 4
	v_lshl_add_u64 v[96:97], s[62:63], 0, v[98:99]
	v_cmp_lt_i32_e32 vcc, s38, v117
	v_mov_b32_dpp v106, v84 row_ror:1 row_mask:0xf bank_mask:0xf
	v_mov_b32_dpp v107, v85 row_ror:1 row_mask:0xf bank_mask:0xf
	v_mov_b32_dpp v108, v86 row_ror:1 row_mask:0xf bank_mask:0xf
	v_mov_b32_dpp v110, v87 row_ror:1 row_mask:0xf bank_mask:0xf
	v_mov_b32_dpp v109, v84 row_ror:2 row_mask:0xf bank_mask:0xf
	v_mov_b32_dpp v111, v85 row_ror:2 row_mask:0xf bank_mask:0xf
	v_mov_b32_dpp v114, v86 row_ror:2 row_mask:0xf bank_mask:0xf
	v_mov_b32_dpp v115, v87 row_ror:2 row_mask:0xf bank_mask:0xf
	v_lshl_add_u64 v[96:97], v[210:211], 2, v[96:97]
	s_and_saveexec_b64 s[0:1], vcc
	s_cbranch_execz .LBB0_968
	global_store_dwordx4 v[96:97], v[84:87], off
.LBB0_968:
	s_or_b64 exec, exec, s[0:1]
	v_pk_add_f32 v[66:67], v[66:67], v[90:91]
	v_pk_add_f32 v[64:65], v[64:65], v[88:89]
	s_nop 7
	v_mov_b32_dpp v98, v64 row_ror:1 row_mask:0xf bank_mask:0xf
	v_mov_b32_dpp v99, v65 row_ror:1 row_mask:0xf bank_mask:0xf
	v_mov_b32_dpp v100, v66 row_ror:1 row_mask:0xf bank_mask:0xf
	v_mov_b32_dpp v102, v67 row_ror:1 row_mask:0xf bank_mask:0xf
	v_mov_b32_dpp v101, v64 row_ror:2 row_mask:0xf bank_mask:0xf
	v_mov_b32_dpp v103, v65 row_ror:2 row_mask:0xf bank_mask:0xf
	v_mov_b32_dpp v104, v66 row_ror:2 row_mask:0xf bank_mask:0xf
	v_mov_b32_dpp v105, v67 row_ror:2 row_mask:0xf bank_mask:0xf
	s_and_saveexec_b64 s[0:1], vcc
	s_cbranch_execz .LBB0_970
	global_store_dwordx4 v[96:97], v[64:67], off offset:16
.LBB0_970:
	s_or_b64 exec, exec, s[0:1]
	v_cmp_gt_i32_e32 vcc, 2, v117
	v_cndmask_b32_e64 v96, v106, v131, s[42:43]
	v_cndmask_b32_e64 v131, v134, v109, s[44:45]
	v_cndmask_b32_e64 v134, v136, v111, s[44:45]
	v_cmp_eq_u32_e64 s[52:53], 0, v117
	v_cndmask_b32_e64 v117, v108, v133, s[42:43]
	v_cndmask_b32_e64 v118, v110, v135, s[42:43]
	v_cndmask_b32_e64 v97, v107, v132, s[42:43]
	v_cndmask_b32_e64 v132, v137, v114, s[44:45]
	v_cndmask_b32_e64 v133, v138, v115, s[44:45]
	v_cndmask_b32_e64 v135, v134, 0, vcc
	v_cndmask_b32_e64 v134, v131, 0, vcc
	v_cndmask_b32_e64 v97, v97, 0, s[52:53]
	v_cndmask_b32_e64 v96, v96, 0, s[52:53]
	v_cndmask_b32_e64 v133, v133, 0, vcc
	v_cndmask_b32_e64 v132, v132, 0, vcc
	v_pk_fma_f32 v[134:135], v[72:73], v[134:135], v[76:77]
	v_cndmask_b32_e64 v119, v118, 0, s[52:53]
	v_cndmask_b32_e64 v118, v117, 0, s[52:53]
	v_pk_fma_f32 v[132:133], v[74:75], v[132:133], v[78:79]
	v_pk_fma_f32 v[96:97], v[68:69], v[96:97], v[134:135]
	v_pk_fma_f32 v[118:119], v[70:71], v[118:119], v[132:133]
	v_pk_fma_f32 v[84:85], v[84:85], v[60:61], v[96:97]
	v_pk_fma_f32 v[86:87], v[86:87], v[62:63], v[118:119]
	v_pk_mul_f32 v[118:119], v[84:85], v[84:85]
	v_mov_b64_e32 v[132:133], s[70:71]
	v_pk_fma_f32 v[118:119], v[118:119], s[68:69], v[132:133] op_sel_hi:[1,0,0] neg_lo:[1,0,0] neg_hi:[1,0,0]
	v_pk_add_f32 v[36:37], v[36:37], v[56:57]
	v_pk_mul_f32 v[118:119], v[84:85], v[118:119]
	v_pk_mul_f32 v[96:97], v[86:87], v[86:87]
	v_exp_f32_e32 v118, v118
	v_exp_f32_e32 v119, v119
	v_pk_add_f32 v[38:39], v[38:39], v[58:59]
	v_cndmask_b32_e64 v117, v124, v101, s[44:45]
	v_pk_add_f32 v[32:33], v[32:33], v[80:81]
	v_pk_add_f32 v[118:119], v[118:119], 1.0 op_sel_hi:[1,0]
	v_pk_add_f32 v[34:35], v[34:35], v[82:83]
	v_rcp_f32_e32 v118, v118
	v_rcp_f32_e32 v119, v119
	v_pk_add_f32 v[30:31], v[30:31], v[94:95]
	v_pk_add_f32 v[28:29], v[28:29], v[92:93]
	v_pk_mul_f32 v[84:85], v[84:85], v[118:119]
	s_nop 0
	v_pk_mul_f32 v[36:37], v[36:37], v[84:85]
	v_pk_fma_f32 v[84:85], v[96:97], s[68:69], v[132:133] op_sel_hi:[1,0,0] neg_lo:[1,0,0] neg_hi:[1,0,0]
	v_cndmask_b32_e64 v118, v126, v103, s[44:45]
	v_pk_mul_f32 v[84:85], v[86:87], v[84:85]
	v_cndmask_b32_e64 v96, v127, v104, s[44:45]
	v_exp_f32_e32 v84, v84
	v_exp_f32_e32 v85, v85
	v_cndmask_b32_e64 v97, v130, v105, s[44:45]
	v_cndmask_b32_e64 v119, v118, 0, vcc
	v_cndmask_b32_e64 v118, v117, 0, vcc
	v_pk_add_f32 v[84:85], v[84:85], 1.0 op_sel_hi:[1,0]
	v_cndmask_b32_e64 v97, v97, 0, vcc
	v_rcp_f32_e32 v84, v84
	v_rcp_f32_e32 v85, v85
	v_cndmask_b32_e64 v96, v96, 0, vcc
	v_pk_fma_f32 v[118:119], v[48:49], v[118:119], v[52:53]
	v_pk_fma_f32 v[96:97], v[50:51], v[96:97], v[54:55]
	v_pk_mul_f32 v[84:85], v[86:87], v[84:85]
	v_cndmask_b32_e64 v86, v100, v123, s[42:43]
	v_pk_mul_f32 v[38:39], v[38:39], v[84:85]
	v_cndmask_b32_e64 v84, v98, v121, s[42:43]
	v_cndmask_b32_e64 v85, v99, v122, s[42:43]
	v_cndmask_b32_e64 v87, v102, v125, s[42:43]
	v_cndmask_b32_e64 v85, v85, 0, s[52:53]
	v_cndmask_b32_e64 v84, v84, 0, s[52:53]
	v_cndmask_b32_e64 v87, v87, 0, s[52:53]
	v_cndmask_b32_e64 v86, v86, 0, s[52:53]
	v_pk_fma_f32 v[84:85], v[44:45], v[84:85], v[118:119]
	v_pk_fma_f32 v[86:87], v[46:47], v[86:87], v[96:97]
	v_pk_fma_f32 v[64:65], v[64:65], v[40:41], v[84:85]
	v_pk_fma_f32 v[66:67], v[66:67], v[42:43], v[86:87]
	v_pk_mul_f32 v[86:87], v[64:65], v[64:65]
	v_pk_mul_f32 v[84:85], v[66:67], v[66:67]
	v_pk_fma_f32 v[86:87], v[86:87], s[68:69], v[132:133] op_sel_hi:[1,0,0] neg_lo:[1,0,0] neg_hi:[1,0,0]
	s_nop 0
	v_pk_mul_f32 v[86:87], v[64:65], v[86:87]
	s_nop 0
	v_exp_f32_e32 v86, v86
	v_exp_f32_e32 v87, v87
	s_nop 0
	v_pk_add_f32 v[86:87], v[86:87], 1.0 op_sel_hi:[1,0]
	s_nop 0
	v_rcp_f32_e32 v86, v86
	v_rcp_f32_e32 v87, v87
	s_nop 0
	v_pk_mul_f32 v[64:65], v[64:65], v[86:87]
	s_nop 0
	v_pk_mul_f32 v[64:65], v[32:33], v[64:65]
	v_pk_fma_f32 v[32:33], v[84:85], s[68:69], v[132:133] op_sel_hi:[1,0,0] neg_lo:[1,0,0] neg_hi:[1,0,0]
	s_nop 0
	v_pk_mul_f32 v[32:33], v[66:67], v[32:33]
	s_nop 0
	v_exp_f32_e32 v32, v32
	v_exp_f32_e32 v33, v33
	s_nop 0
	v_pk_add_f32 v[32:33], v[32:33], 1.0 op_sel_hi:[1,0]
	s_nop 0
	v_rcp_f32_e32 v32, v32
	v_rcp_f32_e32 v33, v33
	s_nop 0
	v_pk_mul_f32 v[32:33], v[66:67], v[32:33]
	s_nop 0
	v_pk_mul_f32 v[66:67], v[34:35], v[32:33]
	v_cvt_pk_bf16_f32 v32, v36, v37
	v_mov_b64_e32 v[36:37], s[86:87]
	v_mad_i64_i32 v[36:37], s[0:1], v116, s40, v[36:37]
	v_lshl_add_u64 v[36:37], v[210:211], 1, v[36:37]
	v_or_b32_e32 v116, 32, v120
	v_cvt_pk_bf16_f32 v33, v38, v39
	v_cvt_pk_bf16_f32 v34, v64, v65
	v_cvt_pk_bf16_f32 v35, v66, v67
	global_store_dwordx4 v[36:37], v[32:35], off
	s_nop 1
	v_mul_hi_i32 v32, v116, s14
	v_lshrrev_b32_e32 v33, 31, v32
	v_ashrrev_i32_e32 v32, 7, v32
	v_add_u32_e32 v32, v32, v33
	v_mad_i32_i24 v117, v32, s15, v116
	v_ashrrev_i32_e32 v33, 31, v32
	v_add_u32_e32 v198, 0xfffff7f2, v117
	v_lshl_add_u64 v[32:33], v[32:33], 1, v[198:199]
	v_mad_u64_u32 v[66:67], s[0:1], v32, s39, 0
	v_mad_i32_i24 v67, v33, s39, v67
	s_nop 5
	v_lshl_add_u64 v[32:33], s[62:63], 0, v[66:67]
	v_cmp_lt_i32_e32 vcc, s38, v117
	v_mov_b32_dpp v34, v28 row_ror:1 row_mask:0xf bank_mask:0xf
	v_mov_b32_dpp v35, v29 row_ror:1 row_mask:0xf bank_mask:0xf
	v_mov_b32_dpp v36, v30 row_ror:1 row_mask:0xf bank_mask:0xf
	v_mov_b32_dpp v37, v31 row_ror:1 row_mask:0xf bank_mask:0xf
	v_mov_b32_dpp v38, v28 row_ror:2 row_mask:0xf bank_mask:0xf
	v_mov_b32_dpp v39, v29 row_ror:2 row_mask:0xf bank_mask:0xf
	v_mov_b32_dpp v64, v30 row_ror:2 row_mask:0xf bank_mask:0xf
	v_mov_b32_dpp v65, v31 row_ror:2 row_mask:0xf bank_mask:0xf
	v_lshl_add_u64 v[32:33], v[210:211], 2, v[32:33]
	s_and_saveexec_b64 s[0:1], vcc
	s_cbranch_execz .LBB0_972
	global_store_dwordx4 v[32:33], v[28:31], off
.LBB0_972:
	s_or_b64 exec, exec, s[0:1]
	v_pk_add_f32 v[26:27], v[26:27], v[90:91]
	v_pk_add_f32 v[24:25], v[24:25], v[88:89]
	s_nop 7
	v_mov_b32_dpp v66, v24 row_ror:1 row_mask:0xf bank_mask:0xf
	v_mov_b32_dpp v67, v25 row_ror:1 row_mask:0xf bank_mask:0xf
	v_mov_b32_dpp v84, v26 row_ror:1 row_mask:0xf bank_mask:0xf
	v_mov_b32_dpp v85, v27 row_ror:1 row_mask:0xf bank_mask:0xf
	v_mov_b32_dpp v86, v24 row_ror:2 row_mask:0xf bank_mask:0xf
	v_mov_b32_dpp v87, v25 row_ror:2 row_mask:0xf bank_mask:0xf
	v_mov_b32_dpp v96, v26 row_ror:2 row_mask:0xf bank_mask:0xf
	v_mov_b32_dpp v97, v27 row_ror:2 row_mask:0xf bank_mask:0xf
	s_and_saveexec_b64 s[0:1], vcc
	s_cbranch_execz .LBB0_974
	global_store_dwordx4 v[32:33], v[24:27], off offset:16
.LBB0_974:
	s_or_b64 exec, exec, s[0:1]
	v_cmp_eq_u32_e64 s[52:53], 0, v117
	v_cmp_gt_i32_e32 vcc, 2, v117
	v_cndmask_b32_e64 v110, v37, v110, s[42:43]
	v_cndmask_b32_e64 v117, v109, v38, s[44:45]
	v_cndmask_b32_e64 v111, v111, v39, s[44:45]
	v_cndmask_b32_e64 v108, v36, v108, s[42:43]
	v_cndmask_b32_e64 v32, v34, v106, s[42:43]
	v_cndmask_b32_e64 v33, v35, v107, s[42:43]
	v_cndmask_b32_e64 v114, v114, v64, s[44:45]
	v_cndmask_b32_e64 v109, v115, v65, s[44:45]
	v_cndmask_b32_e64 v107, v110, 0, s[52:53]
	v_cndmask_b32_e64 v111, v111, 0, vcc
	v_cndmask_b32_e64 v110, v117, 0, vcc
	v_cndmask_b32_e64 v33, v33, 0, s[52:53]
	v_cndmask_b32_e64 v32, v32, 0, s[52:53]
	v_cndmask_b32_e64 v106, v108, 0, s[52:53]
	v_cndmask_b32_e64 v109, v109, 0, vcc
	v_cndmask_b32_e64 v108, v114, 0, vcc
	v_pk_fma_f32 v[110:111], v[72:73], v[110:111], v[76:77]
	v_pk_fma_f32 v[108:109], v[74:75], v[108:109], v[78:79]
	v_pk_fma_f32 v[32:33], v[68:69], v[32:33], v[110:111]
	v_pk_fma_f32 v[106:107], v[70:71], v[106:107], v[108:109]
	v_pk_fma_f32 v[28:29], v[28:29], v[60:61], v[32:33]
	v_pk_fma_f32 v[30:31], v[30:31], v[62:63], v[106:107]
	v_pk_mul_f32 v[106:107], v[28:29], v[28:29]
	v_mov_b64_e32 v[108:109], s[70:71]
	v_pk_fma_f32 v[106:107], v[106:107], s[68:69], v[108:109] op_sel_hi:[1,0,0] neg_lo:[1,0,0] neg_hi:[1,0,0]
	v_pk_add_f32 v[20:21], v[20:21], v[56:57]
	v_pk_mul_f32 v[106:107], v[28:29], v[106:107]
	v_pk_mul_f32 v[32:33], v[30:31], v[30:31]
	v_exp_f32_e32 v106, v106
	v_exp_f32_e32 v107, v107
	v_pk_add_f32 v[22:23], v[22:23], v[58:59]
	v_pk_add_f32 v[16:17], v[16:17], v[80:81]
	v_pk_add_f32 v[18:19], v[18:19], v[82:83]
	v_pk_add_f32 v[106:107], v[106:107], 1.0 op_sel_hi:[1,0]
	v_pk_add_f32 v[14:15], v[14:15], v[94:95]
	v_rcp_f32_e32 v106, v106
	v_rcp_f32_e32 v107, v107
	v_pk_add_f32 v[12:13], v[12:13], v[92:93]
	v_pk_mul_f32 v[28:29], v[28:29], v[106:107]
	s_nop 0
	v_pk_mul_f32 v[20:21], v[20:21], v[28:29]
	v_pk_fma_f32 v[28:29], v[32:33], s[68:69], v[108:109] op_sel_hi:[1,0,0] neg_lo:[1,0,0] neg_hi:[1,0,0]
	v_cndmask_b32_e64 v32, v104, v96, s[44:45]
	v_pk_mul_f32 v[28:29], v[30:31], v[28:29]
	v_cndmask_b32_e64 v33, v105, v97, s[44:45]
	v_exp_f32_e32 v28, v28
	v_exp_f32_e32 v29, v29
	v_cndmask_b32_e64 v33, v33, 0, vcc
	v_cndmask_b32_e64 v32, v32, 0, vcc
	v_pk_fma_f32 v[32:33], v[50:51], v[32:33], v[54:55]
	v_pk_add_f32 v[28:29], v[28:29], 1.0 op_sel_hi:[1,0]
	s_nop 0
	v_rcp_f32_e32 v28, v28
	v_rcp_f32_e32 v29, v29
	s_nop 0
	v_pk_mul_f32 v[28:29], v[30:31], v[28:29]
	s_nop 0
	v_pk_mul_f32 v[22:23], v[22:23], v[28:29]
	v_cndmask_b32_e64 v28, v66, v98, s[42:43]
	v_cndmask_b32_e64 v29, v67, v99, s[42:43]
	v_cndmask_b32_e64 v98, v101, v86, s[44:45]
	v_cndmask_b32_e64 v99, v103, v87, s[44:45]
	v_cndmask_b32_e64 v99, v99, 0, vcc
	v_cndmask_b32_e64 v98, v98, 0, vcc
	v_cndmask_b32_e64 v30, v84, v100, s[42:43]
	v_cndmask_b32_e64 v31, v85, v102, s[42:43]
	v_cndmask_b32_e64 v29, v29, 0, s[52:53]
	v_cndmask_b32_e64 v28, v28, 0, s[52:53]
	v_pk_fma_f32 v[98:99], v[48:49], v[98:99], v[52:53]
	v_cndmask_b32_e64 v31, v31, 0, s[52:53]
	v_cndmask_b32_e64 v30, v30, 0, s[52:53]
	v_pk_fma_f32 v[28:29], v[44:45], v[28:29], v[98:99]
	v_pk_fma_f32 v[30:31], v[46:47], v[30:31], v[32:33]
	v_pk_fma_f32 v[24:25], v[24:25], v[40:41], v[28:29]
	v_pk_fma_f32 v[26:27], v[26:27], v[42:43], v[30:31]
	v_pk_mul_f32 v[30:31], v[24:25], v[24:25]
	v_pk_mul_f32 v[28:29], v[26:27], v[26:27]
	v_pk_fma_f32 v[30:31], v[30:31], s[68:69], v[108:109] op_sel_hi:[1,0,0] neg_lo:[1,0,0] neg_hi:[1,0,0]
	s_nop 0
	v_pk_mul_f32 v[30:31], v[24:25], v[30:31]
	s_nop 0
	v_exp_f32_e32 v30, v30
	v_exp_f32_e32 v31, v31
	s_nop 0
	v_pk_add_f32 v[30:31], v[30:31], 1.0 op_sel_hi:[1,0]
	s_nop 0
	v_rcp_f32_e32 v30, v30
	v_rcp_f32_e32 v31, v31
	s_nop 0
	v_pk_mul_f32 v[24:25], v[24:25], v[30:31]
	s_nop 0
	v_pk_mul_f32 v[24:25], v[16:17], v[24:25]
	v_pk_fma_f32 v[16:17], v[28:29], s[68:69], v[108:109] op_sel_hi:[1,0,0] neg_lo:[1,0,0] neg_hi:[1,0,0]
	s_nop 0
	v_pk_mul_f32 v[16:17], v[26:27], v[16:17]
	s_nop 0
	v_exp_f32_e32 v16, v16
	v_exp_f32_e32 v17, v17
	s_nop 0
	v_pk_add_f32 v[16:17], v[16:17], 1.0 op_sel_hi:[1,0]
	s_nop 0
	v_rcp_f32_e32 v16, v16
	v_rcp_f32_e32 v17, v17
	s_nop 0
	v_pk_mul_f32 v[16:17], v[26:27], v[16:17]
	s_nop 0
	v_pk_mul_f32 v[26:27], v[18:19], v[16:17]
	v_cvt_pk_bf16_f32 v16, v20, v21
	v_mov_b64_e32 v[20:21], s[86:87]
	v_mad_i64_i32 v[20:21], s[0:1], v116, s40, v[20:21]
	v_cvt_pk_bf16_f32 v17, v22, v23
	v_cvt_pk_bf16_f32 v18, v24, v25
	v_lshl_add_u64 v[20:21], v[210:211], 1, v[20:21]
	v_cvt_pk_bf16_f32 v19, v26, v27
	global_store_dwordx4 v[20:21], v[16:19], off
	s_nop 1
	v_or_b32_e32 v18, 48, v120
	v_mul_hi_i32 v16, v18, s14
	v_lshrrev_b32_e32 v17, 31, v16
	v_ashrrev_i32_e32 v16, 7, v16
	v_add_u32_e32 v16, v16, v17
	v_mad_i32_i24 v19, v16, s15, v18
	v_ashrrev_i32_e32 v17, 31, v16
	v_add_u32_e32 v198, 0xfffff7f2, v19
	v_lshl_add_u64 v[16:17], v[16:17], 1, v[198:199]
	v_mad_u64_u32 v[28:29], s[4:5], v16, s39, 0
	v_mad_i32_i24 v29, v17, s39, v29
	s_nop 5
	v_lshl_add_u64 v[16:17], s[62:63], 0, v[28:29]
	v_cmp_lt_i32_e64 s[0:1], s38, v19
	v_mov_b32_dpp v20, v12 row_ror:1 row_mask:0xf bank_mask:0xf
	v_mov_b32_dpp v21, v13 row_ror:1 row_mask:0xf bank_mask:0xf
	v_mov_b32_dpp v22, v14 row_ror:1 row_mask:0xf bank_mask:0xf
	v_mov_b32_dpp v23, v15 row_ror:1 row_mask:0xf bank_mask:0xf
	v_mov_b32_dpp v24, v12 row_ror:2 row_mask:0xf bank_mask:0xf
	v_mov_b32_dpp v25, v13 row_ror:2 row_mask:0xf bank_mask:0xf
	v_mov_b32_dpp v26, v14 row_ror:2 row_mask:0xf bank_mask:0xf
	v_mov_b32_dpp v27, v15 row_ror:2 row_mask:0xf bank_mask:0xf
	v_lshl_add_u64 v[16:17], v[210:211], 2, v[16:17]
	s_and_saveexec_b64 s[30:31], s[0:1]
	s_cbranch_execz .LBB0_976
	global_store_dwordx4 v[16:17], v[12:15], off

.LBB0_978:
	s_or_b64 exec, exec, s[30:31]
	v_pk_add_f32 v[10:11], v[10:11], v[90:91]
	v_pk_add_f32 v[8:9], v[8:9], v[88:89]
	s_nop 7
	v_mov_b32_dpp v28, v8 row_ror:1 row_mask:0xf bank_mask:0xf
	v_mov_b32_dpp v29, v9 row_ror:1 row_mask:0xf bank_mask:0xf
	v_mov_b32_dpp v30, v10 row_ror:1 row_mask:0xf bank_mask:0xf
	v_mov_b32_dpp v31, v11 row_ror:1 row_mask:0xf bank_mask:0xf
	v_mov_b32_dpp v32, v8 row_ror:2 row_mask:0xf bank_mask:0xf
	v_mov_b32_dpp v33, v9 row_ror:2 row_mask:0xf bank_mask:0xf
	v_mov_b32_dpp v88, v10 row_ror:2 row_mask:0xf bank_mask:0xf
	v_mov_b32_dpp v89, v11 row_ror:2 row_mask:0xf bank_mask:0xf
	s_and_saveexec_b64 s[30:31], s[0:1]
	s_cbranch_execz .LBB0_980
	global_store_dwordx4 v[16:17], v[8:11], off offset:16
